# all 64 xor16/xor32 epilogue reductions + attention unit reductions via permlane swaps; ranking rewrite; census; balance; rstd
# baseline (speedup 1.0000x reference)
; __device__ __forceinline__ float sigm(float x) { return __builtin_amdgcn_rcpf(1.f + __expf(-x)); }
; __device__ __forceinline__ float gelu_tanh(float x) { return x * sigm(1.5957691216f * (x + 0.044715f * x * x * x)); }
; __device__ __forceinline__ u32x4 pack8(const float* v) { u32x4 w; w.x = cvtpk(v[0], v[1]); w.y = cvtpk(v[2], v[3]); w.z = cvtpk(v[4], v[5]); w.w = cvtpk(v[6], v[7]); return w; }
;     template <int KIND>
;     __device__ __forceinline__ void act_tile(const pg8::f32x4 (&acc)[2][2][4][2], const float (&rs)[2][4], unsigned char* w_, int row0, int colt, int statslot, int fq_) const {
;     ...
;         for (int ai = 0; ai < 2; ++ai)
; #pragma unroll
;             for (int m = 0; m < 4; ++m) {
;                 const int row = row0 + ai * 128 + m * 16;
;                 float s1 = 0.f, s2 = 0.f;
; #pragma unroll
;                 for (int bj = 0; bj < 2; ++bj) {
;                     float v[8];
; #pragma unroll
;                     for (int n = 0; n < 2; ++n)
; #pragma unroll
;                         for (int j = 0; j < 4; ++j) {
;                             const float a = acc[ai][bj][m][n][j] * rs[ai][m];
;                             const float r = KIND == 2 ? sigm(a) : gelu_tanh(a);
;                             v[n * 4 + j] = r;
;                             if (KIND == 1) { s1 += r; s2 += r * r; }
;                         }
;                     *(u32x4*)(base + (size_t)row * ldc + colt + bj * 128) = pack8(v);
;                 }
;                 if (KIND == 1) {
;                     s1 += __shfl_xor(s1, 16); s1 += __shfl_xor(s1, 32); s2 += __shfl_xor(s2, 16); s2 += __shfl_xor(s2, 32);
;     __device__ __forceinline__ void operator()(const pg8::f32x4 (&acc)[2][2][4][2], const pg8::Unit& u, int wr, int wc, int fr, int fq) const {
;     ...
;             else if (pn < 18) act_tile<1>(acc, rs, w_, row0, (pn - 14) * 256 + wc * 32 + fq_ * 8, (pn - 14) * 4 + wc, fq_);
.LBB0_871:
	s_andn2_b64 vcc, exec, s[0:1]
	s_cbranch_vccnz .LBB0_889
	s_waitcnt lgkmcnt(0)
	v_pk_mul_f32 v[138:139], v[126:127], v[164:165] op_sel_hi:[1,0]
	v_pk_mul_f32 v[142:143], v[128:129], v[164:165] op_sel_hi:[1,0]
	v_mul_f32_e32 v140, 0x3d372713, v138
	v_mul_f32_e32 v141, 0x3d372713, v139
	v_mul_f32_e32 v140, v138, v140
	v_mul_f32_e32 v141, v139, v141
	v_fma_f32 v140, v138, v140, v138
	v_fma_f32 v141, v139, v141, v139
	v_mul_f32_e32 v144, 0x3d372713, v142
	v_mul_f32_e32 v145, 0x3d372713, v143
	v_mul_f32_e32 v140, 0x3fcc422a, v140
	v_mul_f32_e32 v141, 0x3fcc422a, v141
	v_mul_f32_e32 v144, v142, v144
	v_mul_f32_e32 v145, v143, v145
	v_mul_f32_e32 v140, 0xbfb8aa3b, v140
	v_mul_f32_e32 v141, 0xbfb8aa3b, v141
	v_fma_f32 v144, v142, v144, v142
	v_fma_f32 v145, v143, v145, v143
	v_exp_f32_e32 v140, v140
	v_exp_f32_e32 v141, v141
	v_mul_f32_e32 v144, 0x3fcc422a, v144
	v_mul_f32_e32 v145, 0x3fcc422a, v145
	v_mul_f32_e32 v144, 0xbfb8aa3b, v144
	v_mul_f32_e32 v145, 0xbfb8aa3b, v145
	v_exp_f32_e32 v144, v144
	v_exp_f32_e32 v145, v145
	v_add_f32_e32 v140, 1.0, v140
	v_add_f32_e32 v141, 1.0, v141
	v_rcp_f32_e32 v140, v140
	v_rcp_f32_e32 v141, v141
	v_add_f32_e32 v144, 1.0, v144
	v_add_f32_e32 v145, 1.0, v145
	v_and_b32_e32 v131, 64, v226
	v_rcp_f32_e32 v144, v144
	v_rcp_f32_e32 v145, v145
	v_xor_b32_e32 v0, 16, v226
	v_add_u32_e32 v136, 64, v131
	v_cmp_lt_i32_e32 vcc, v0, v136
	v_pk_mul_f32 v[138:139], v[138:139], v[140:141]
	v_pk_mul_f32 v[142:143], v[142:143], v[144:145]
	v_cndmask_b32_e32 v0, v226, v0, vcc
	v_add_f32_e32 v140, 0, v138
	v_lshlrev_b32_e32 v131, 2, v0
	v_xor_b32_e32 v0, 32, v226
	v_add_f32_e32 v166, v139, v140
	v_cmp_lt_i32_e32 vcc, v0, v136
	v_add_f32_e32 v144, v142, v166
	v_mul_f32_e32 v140, v139, v139
	v_cndmask_b32_e32 v0, v226, v0, vcc
	v_cmp_eq_u32_e32 vcc, 0, v168
	v_add_f32_e32 v168, v143, v144
	v_pk_mul_f32 v[144:145], v[122:123], v[164:165] op_sel_hi:[1,0]
	v_pk_fma_f32 v[140:141], v[138:139], v[138:139], v[140:141] op_sel_hi:[1,1,0]
	v_mul_f32_e32 v166, 0x3d372713, v144
	v_mul_f32_e32 v167, 0x3d372713, v145
	v_mul_f32_e32 v166, v144, v166
	v_mul_f32_e32 v167, v145, v167
	v_fma_f32 v166, v144, v166, v144
	v_fma_f32 v167, v145, v167, v145
	v_mul_f32_e32 v166, 0x3fcc422a, v166
	v_mul_f32_e32 v167, 0x3fcc422a, v167
	v_mul_f32_e32 v166, 0xbfb8aa3b, v166
	v_mul_f32_e32 v167, 0xbfb8aa3b, v167
	v_exp_f32_e32 v166, v166
	v_exp_f32_e32 v167, v167
	v_pk_fma_f32 v[140:141], v[142:143], v[142:143], v[140:141]
	s_add_i32 s0, s66, -14
	v_add_f32_e32 v166, 1.0, v166
	v_add_f32_e32 v167, 1.0, v167
	v_rcp_f32_e32 v166, v166
	v_rcp_f32_e32 v167, v167
	s_lshl_b32 s1, s0, 8
	v_readlane_b32 s2, v255, 46
	s_or_b32 s1, s1, s2
	v_pk_mul_f32 v[144:145], v[144:145], v[166:167]
	v_mov_b32_e32 v167, v143
	v_add_f32_e32 v169, v144, v168
	v_mul_f32_e32 v168, v143, v143
	v_mov_b32_e32 v166, v144
	v_pk_add_f32 v[140:141], v[168:169], v[140:141] op_sel_hi:[0,1]
	v_pk_fma_f32 v[140:141], v[166:167], v[166:167], v[140:141]
	v_pk_mul_f32 v[166:167], v[124:125], v[164:165] op_sel_hi:[1,0]
	v_add_f32_e32 v170, v145, v169
	v_mul_f32_e32 v168, 0x3d372713, v166
	v_mul_f32_e32 v169, 0x3d372713, v167
	v_mul_f32_e32 v168, v166, v168
	v_mul_f32_e32 v169, v167, v169
	v_fma_f32 v168, v166, v168, v166
	v_fma_f32 v169, v167, v169, v167
	v_mul_f32_e32 v168, 0x3fcc422a, v168
	v_mul_f32_e32 v169, 0x3fcc422a, v169
	v_mul_f32_e32 v168, 0xbfb8aa3b, v168
	v_mul_f32_e32 v169, 0xbfb8aa3b, v169
	v_exp_f32_e32 v168, v168
	v_exp_f32_e32 v169, v169
	v_add_u32_e32 v134, s1, v130
	v_ashrrev_i32_e32 v135, 31, v134
	v_add_f32_e32 v168, 1.0, v168
	v_add_f32_e32 v169, 1.0, v169
	v_rcp_f32_e32 v168, v168
	v_rcp_f32_e32 v169, v169
	v_lshl_add_u64 v[134:135], v[134:135], 1, s[74:75]
	s_mov_b64 s[10:11], 0x1c4b6800
	v_lshl_add_u64 v[134:135], v[134:135], 0, s[10:11]
	v_pk_mul_f32 v[166:167], v[166:167], v[168:169]
	v_lshlrev_b64 v[136:137], 11, v[158:159]
	v_add_f32_e32 v171, v166, v170
	v_mul_f32_e32 v170, v145, v145
	v_mov_b32_e32 v168, v166
	v_mov_b32_e32 v169, v145
	v_pk_add_f32 v[140:141], v[170:171], v[140:141] op_sel_hi:[0,1]
	v_lshl_add_u64 v[136:137], v[134:135], 0, v[136:137]
	v_pk_fma_f32 v[168:169], v[168:169], v[168:169], v[140:141]
	v_cvt_pk_bf16_f32 v138, v138, v139
	v_cvt_pk_bf16_f32 v139, v142, v143
	v_cvt_pk_bf16_f32 v140, v144, v145
	v_cvt_pk_bf16_f32 v141, v166, v167
	global_store_dwordx4 v[136:137], v[138:141], off
	v_add_f32_e32 v170, v167, v171
	s_lshl_b32 s0, s0, 3
	v_pk_mul_f32 v[138:139], v[118:119], v[164:165] op_sel_hi:[1,0]
	v_readlane_b32 s1, v255, 49
	v_mul_f32_e32 v140, 0x3d372713, v138
	v_mul_f32_e32 v141, 0x3d372713, v139
	v_mul_f32_e32 v140, v138, v140
	v_mul_f32_e32 v141, v139, v141
	v_fma_f32 v140, v138, v140, v138
	v_fma_f32 v141, v139, v141, v139
	v_mul_f32_e32 v140, 0x3fcc422a, v140
	v_mul_f32_e32 v141, 0x3fcc422a, v141
	v_mul_f32_e32 v140, 0xbfb8aa3b, v140
	v_mul_f32_e32 v141, 0xbfb8aa3b, v141
	v_exp_f32_e32 v140, v140
	v_exp_f32_e32 v141, v141
	v_lshlrev_b32_e32 v0, 2, v0
	s_or_b32 s38, s0, s1
	v_add_f32_e32 v140, 1.0, v140
	v_add_f32_e32 v141, 1.0, v141
	v_rcp_f32_e32 v140, v140
	v_rcp_f32_e32 v141, v141
	s_lshl_b64 s[0:1], s[38:39], 2
	s_add_u32 s0, s74, s0
	s_addc_u32 s1, s75, s1
	v_pk_mul_f32 v[138:139], v[138:139], v[140:141]
	v_mul_f32_e32 v140, v167, v167
	v_add_f32_e32 v142, v138, v170
	v_mov_b32_e32 v166, v138
	v_pk_add_f32 v[140:141], v[140:141], v[168:169] op_sel_hi:[0,1]
	v_pk_fma_f32 v[140:141], v[166:167], v[166:167], v[140:141]
	v_add_f32_e32 v166, v139, v142
	v_pk_mul_f32 v[142:143], v[120:121], v[164:165] op_sel_hi:[1,0]
	v_cvt_pk_bf16_f32 v138, v138, v139
	v_mul_f32_e32 v144, 0x3d372713, v142
	v_mul_f32_e32 v145, 0x3d372713, v143
; __device__ __forceinline__ float sigm(float x) { return __builtin_amdgcn_rcpf(1.f + __expf(-x)); }
; __device__ __forceinline__ float gelu_tanh(float x) { return x * sigm(1.5957691216f * (x + 0.044715f * x * x * x)); }
; __device__ __forceinline__ u32x4 pack8(const float* v) { u32x4 w; w.x = cvtpk(v[0], v[1]); w.y = cvtpk(v[2], v[3]); w.z = cvtpk(v[4], v[5]); w.w = cvtpk(v[6], v[7]); return w; }
;     template <int KIND>
;     __device__ __forceinline__ void act_tile(const pg8::f32x4 (&acc)[2][2][4][2], const float (&rs)[2][4], unsigned char* w_, int row0, int colt, int statslot, int fq_) const {
;     ...
;                 for (int bj = 0; bj < 2; ++bj) {
;                     float v[8];
; #pragma unroll
;                     for (int n = 0; n < 2; ++n)
; #pragma unroll
;                         for (int j = 0; j < 4; ++j) {
;                             const float a = acc[ai][bj][m][n][j] * rs[ai][m];
;                             const float r = KIND == 2 ? sigm(a) : gelu_tanh(a);
;                             v[n * 4 + j] = r;
;                             if (KIND == 1) { s1 += r; s2 += r * r; }
;                         }
;                     *(u32x4*)(base + (size_t)row * ldc + colt + bj * 128) = pack8(v);
;                 }
;                 if (KIND == 1) {
;                     s1 += __shfl_xor(s1, 16); s1 += __shfl_xor(s1, 32); s2 += __shfl_xor(s2, 16); s2 += __shfl_xor(s2, 32);
;                     if (fq_ == 0) { float* sp = (float*)(w_ + WS_VSTAT) + ((size_t)row * 16 + statslot) * 2; sp[0] = s1; sp[1] = s2; }
;                 }
	v_mul_f32_e32 v144, v142, v144
	v_mul_f32_e32 v145, v143, v145
	v_fma_f32 v144, v142, v144, v142
	v_fma_f32 v145, v143, v145, v143
	v_mul_f32_e32 v144, 0x3fcc422a, v144
	v_mul_f32_e32 v145, 0x3fcc422a, v145
	v_mul_f32_e32 v144, 0xbfb8aa3b, v144
	v_mul_f32_e32 v145, 0xbfb8aa3b, v145
	v_exp_f32_e32 v144, v144
	v_exp_f32_e32 v145, v145
	s_add_u32 s0, s0, 0x21636800
	s_addc_u32 s1, s1, 0
	v_add_f32_e32 v144, 1.0, v144
	v_add_f32_e32 v145, 1.0, v145
	v_rcp_f32_e32 v144, v144
	v_rcp_f32_e32 v145, v145
	s_nop 0
	v_pk_mul_f32 v[142:143], v[142:143], v[144:145]
	s_nop 0
	v_add_f32_e32 v167, v142, v166
	v_mul_f32_e32 v166, v139, v139
	v_mov_b32_e32 v144, v142
	v_mov_b32_e32 v145, v139
	v_pk_add_f32 v[140:141], v[166:167], v[140:141] op_sel_hi:[0,1]
	v_pk_fma_f32 v[140:141], v[144:145], v[144:145], v[140:141]
	v_pk_mul_f32 v[144:145], v[114:115], v[164:165] op_sel_hi:[1,0]
	v_add_f32_e32 v168, v143, v167
	v_mul_f32_e32 v166, 0x3d372713, v144
	v_mul_f32_e32 v167, 0x3d372713, v145
	v_mul_f32_e32 v166, v144, v166
	v_mul_f32_e32 v167, v145, v167
	v_fma_f32 v166, v144, v166, v144
	v_fma_f32 v167, v145, v167, v145
	v_mul_f32_e32 v166, 0x3fcc422a, v166
	v_mul_f32_e32 v167, 0x3fcc422a, v167
	v_mul_f32_e32 v166, 0xbfb8aa3b, v166
	v_mul_f32_e32 v167, 0xbfb8aa3b, v167
	v_exp_f32_e32 v166, v166
	v_exp_f32_e32 v167, v167
	v_cvt_pk_bf16_f32 v139, v142, v143
	v_add_f32_e32 v166, 1.0, v166
	v_add_f32_e32 v167, 1.0, v167
	v_rcp_f32_e32 v166, v166
	v_rcp_f32_e32 v167, v167
	s_nop 0
	v_pk_mul_f32 v[144:145], v[144:145], v[166:167]
	s_nop 0
	v_add_f32_e32 v169, v144, v168
	v_mul_f32_e32 v168, v143, v143
	v_mov_b32_e32 v166, v144
	v_mov_b32_e32 v167, v143
	v_pk_add_f32 v[140:141], v[168:169], v[140:141] op_sel_hi:[0,1]
	v_pk_mul_f32 v[142:143], v[116:117], v[164:165] op_sel_hi:[1,0]
	v_pk_fma_f32 v[166:167], v[166:167], v[166:167], v[140:141]
	v_mul_f32_e32 v141, 0x3d372713, v142
	v_mul_f32_e32 v141, v142, v141
	v_fma_f32 v141, v142, v141, v142
	v_mul_f32_e32 v141, 0x3fcc422a, v141
	v_mul_f32_e32 v141, 0xbfb8aa3b, v141
	v_exp_f32_e32 v141, v141
	v_mul_f32_e32 v174, v145, v145
	v_add_f32_e32 v168, v145, v169
	v_cvt_pk_bf16_f32 v140, v144, v145
	v_add_f32_e32 v141, 1.0, v141
	v_rcp_f32_e32 v170, v141
	v_mul_f32_e32 v141, 0x3d372713, v143
	v_mul_f32_e32 v141, v143, v141
	v_fma_f32 v141, v143, v141, v143
	v_mul_f32_e32 v141, 0x3fcc422a, v141
	v_mul_f32_e32 v141, 0xbfb8aa3b, v141
	v_exp_f32_e32 v141, v141
	v_pk_add_f32 v[166:167], v[174:175], v[166:167] op_sel_hi:[0,1]
	v_add_f32_e32 v141, 1.0, v141
	v_rcp_f32_e32 v171, v141
	s_nop 0
	v_pk_mul_f32 v[172:173], v[142:143], v[170:171]
	s_nop 0
	v_mov_b32_e32 v144, v172
	v_mov_b32_e32 v169, v173
	v_pk_fma_f32 v[144:145], v[144:145], v[144:145], v[166:167]
	v_pk_fma_f32 v[142:143], v[142:143], v[170:171], v[168:169]
	v_pk_mul_f32 v[166:167], v[172:173], v[172:173]
	v_pk_mov_b32 v[144:145], v[172:173], v[144:145] op_sel:[1,0]
	v_mov_b32_e32 v143, v167
	v_pk_add_f32 v[142:143], v[142:143], v[144:145]
	v_cvt_pk_bf16_f32 v141, v172, v173
	global_store_dwordx4 v[136:137], v[138:141], off offset:256
	v_mov_b32_e32 v136, v142
	s_nop 1
	v_permlane16_swap_b32_e32 v136, v142
	v_mov_b32_e32 v137, v143
	s_nop 1
	v_permlane16_swap_b32_e32 v137, v143
	s_waitcnt lgkmcnt(0)
	v_pk_add_f32 v[136:137], v[142:143], v[136:137]
	s_nop 0
	v_mov_b32_e32 v138, v136
	s_nop 1
	v_permlane32_swap_b32_e32 v138, v136
	v_mov_b32_e32 v139, v137
	s_nop 1
	v_permlane32_swap_b32_e32 v139, v137
	s_and_saveexec_b64 s[10:11], vcc
	s_cbranch_execz .LBB0_874
	v_lshlrev_b64 v[140:141], 7, v[158:159]
	v_lshl_add_u64 v[140:141], s[0:1], 0, v[140:141]
	s_waitcnt lgkmcnt(0)
	v_pk_add_f32 v[136:137], v[136:137], v[138:139]
	global_store_dwordx2 v[140:141], v[136:137], off
.LBB0_874:
	s_or_b64 exec, exec, s[10:11]
	v_pk_mul_f32 v[140:141], v[110:111], v[164:165] op_sel:[0,1]
	v_pk_mul_f32 v[144:145], v[112:113], v[164:165] op_sel:[0,1]
	v_mul_f32_e32 v142, 0x3d372713, v140
	v_mul_f32_e32 v143, 0x3d372713, v141
	v_mul_f32_e32 v142, v140, v142
	v_mul_f32_e32 v143, v141, v143
	v_fma_f32 v142, v140, v142, v140
	v_fma_f32 v143, v141, v143, v141
	v_mul_f32_e32 v166, 0x3d372713, v144
	v_mul_f32_e32 v167, 0x3d372713, v145
	v_mul_f32_e32 v142, 0x3fcc422a, v142
	v_mul_f32_e32 v143, 0x3fcc422a, v143
	v_mul_f32_e32 v166, v144, v166
	v_mul_f32_e32 v167, v145, v167
	v_mul_f32_e32 v142, 0xbfb8aa3b, v142
	v_mul_f32_e32 v143, 0xbfb8aa3b, v143
	v_fma_f32 v166, v144, v166, v144
	v_fma_f32 v167, v145, v167, v145
	v_exp_f32_e32 v142, v142
	v_exp_f32_e32 v143, v143
	v_mul_f32_e32 v166, 0x3fcc422a, v166
	v_mul_f32_e32 v167, 0x3fcc422a, v167
	v_mul_f32_e32 v166, 0xbfb8aa3b, v166
	v_mul_f32_e32 v167, 0xbfb8aa3b, v167
	v_exp_f32_e32 v166, v166
	v_exp_f32_e32 v167, v167
	v_add_f32_e32 v142, 1.0, v142
	v_add_f32_e32 v143, 1.0, v143
	v_rcp_f32_e32 v142, v142
	v_rcp_f32_e32 v143, v143
	v_add_f32_e32 v166, 1.0, v166
	v_add_f32_e32 v167, 1.0, v167
	v_rcp_f32_e32 v166, v166
	v_rcp_f32_e32 v167, v167
	v_pk_mul_f32 v[140:141], v[140:141], v[142:143]
	v_add_u32_e32 v136, 16, v158
	v_add_f32_e32 v142, 0, v140
	v_add_f32_e32 v168, v141, v142
	v_pk_mul_f32 v[144:145], v[144:145], v[166:167]
	v_mul_f32_e32 v142, v141, v141
	v_add_f32_e32 v166, v144, v168
	v_add_f32_e32 v170, v145, v166
	v_pk_mul_f32 v[166:167], v[106:107], v[164:165] op_sel:[0,1]
	v_pk_fma_f32 v[142:143], v[140:141], v[140:141], v[142:143] op_sel_hi:[1,1,0]
	v_mul_f32_e32 v168, 0x3d372713, v166
	v_mul_f32_e32 v169, 0x3d372713, v167
	v_mul_f32_e32 v168, v166, v168
	v_mul_f32_e32 v169, v167, v169
	v_fma_f32 v168, v166, v168, v166
	v_fma_f32 v169, v167, v169, v167
	v_mul_f32_e32 v168, 0x3fcc422a, v168
	v_mul_f32_e32 v169, 0x3fcc422a, v169
	v_mul_f32_e32 v168, 0xbfb8aa3b, v168
	v_mul_f32_e32 v169, 0xbfb8aa3b, v169
	v_exp_f32_e32 v168, v168
	v_exp_f32_e32 v169, v169
	v_pk_fma_f32 v[142:143], v[144:145], v[144:145], v[142:143]
	v_ashrrev_i32_e32 v137, 31, v136
	v_add_f32_e32 v168, 1.0, v168
	v_add_f32_e32 v169, 1.0, v169
	v_rcp_f32_e32 v168, v168
	v_rcp_f32_e32 v169, v169
	s_waitcnt lgkmcnt(0)
; __device__ __forceinline__ float sigm(float x) { return __builtin_amdgcn_rcpf(1.f + __expf(-x)); }
; __device__ __forceinline__ float gelu_tanh(float x) { return x * sigm(1.5957691216f * (x + 0.044715f * x * x * x)); }
; __device__ __forceinline__ u32x4 pack8(const float* v) { u32x4 w; w.x = cvtpk(v[0], v[1]); w.y = cvtpk(v[2], v[3]); w.z = cvtpk(v[4], v[5]); w.w = cvtpk(v[6], v[7]); return w; }
;     template <int KIND>
;     __device__ __forceinline__ void act_tile(const pg8::f32x4 (&acc)[2][2][4][2], const float (&rs)[2][4], unsigned char* w_, int row0, int colt, int statslot, int fq_) const {
;     ...
;         for (int ai = 0; ai < 2; ++ai)
; #pragma unroll
;             for (int m = 0; m < 4; ++m) {
;                 const int row = row0 + ai * 128 + m * 16;
;                 float s1 = 0.f, s2 = 0.f;
; #pragma unroll
;                 for (int bj = 0; bj < 2; ++bj) {
;                     float v[8];
; #pragma unroll
;                     for (int n = 0; n < 2; ++n)
; #pragma unroll
;                         for (int j = 0; j < 4; ++j) {
;                             const float a = acc[ai][bj][m][n][j] * rs[ai][m];
;                             const float r = KIND == 2 ? sigm(a) : gelu_tanh(a);
;                             v[n * 4 + j] = r;
;                             if (KIND == 1) { s1 += r; s2 += r * r; }
;                         }
;                     *(u32x4*)(base + (size_t)row * ldc + colt + bj * 128) = pack8(v);
;                 }
;                 if (KIND == 1) {
;                     s1 += __shfl_xor(s1, 16); s1 += __shfl_xor(s1, 32); s2 += __shfl_xor(s2, 16); s2 += __shfl_xor(s2, 32);
;                     if (fq_ == 0) { float* sp = (float*)(w_ + WS_VSTAT) + ((size_t)row * 16 + statslot) * 2; sp[0] = s1; sp[1] = s2; }
;                 }
	v_lshlrev_b64 v[138:139], 11, v[136:137]
	v_lshl_add_u64 v[138:139], v[134:135], 0, v[138:139]
	v_cvt_pk_bf16_f32 v140, v140, v141
	v_pk_mul_f32 v[166:167], v[166:167], v[168:169]
	v_mov_b32_e32 v169, v145
	v_add_f32_e32 v171, v166, v170
	v_mul_f32_e32 v170, v145, v145
	v_mov_b32_e32 v168, v166
	v_pk_add_f32 v[142:143], v[170:171], v[142:143] op_sel_hi:[0,1]
	v_pk_fma_f32 v[142:143], v[168:169], v[168:169], v[142:143]
	v_pk_mul_f32 v[168:169], v[108:109], v[164:165] op_sel:[0,1]
	v_add_f32_e32 v172, v167, v171
	v_mul_f32_e32 v170, 0x3d372713, v168
	v_mul_f32_e32 v171, 0x3d372713, v169
	v_mul_f32_e32 v170, v168, v170
	v_mul_f32_e32 v171, v169, v171
	v_fma_f32 v170, v168, v170, v168
	v_fma_f32 v171, v169, v171, v169
	v_mul_f32_e32 v170, 0x3fcc422a, v170
	v_mul_f32_e32 v171, 0x3fcc422a, v171
	v_mul_f32_e32 v170, 0xbfb8aa3b, v170
	v_mul_f32_e32 v171, 0xbfb8aa3b, v171
	v_exp_f32_e32 v170, v170
	v_exp_f32_e32 v171, v171
	v_cvt_pk_bf16_f32 v141, v144, v145
	v_add_f32_e32 v170, 1.0, v170
	v_add_f32_e32 v171, 1.0, v171
	v_rcp_f32_e32 v170, v170
	v_rcp_f32_e32 v171, v171
	s_nop 0
	v_pk_mul_f32 v[168:169], v[168:169], v[170:171]
	s_nop 0
	v_add_f32_e32 v173, v168, v172
	v_mul_f32_e32 v172, v167, v167
	v_mov_b32_e32 v170, v168
	v_mov_b32_e32 v171, v167
	v_pk_add_f32 v[142:143], v[172:173], v[142:143] op_sel_hi:[0,1]
	v_pk_fma_f32 v[170:171], v[170:171], v[170:171], v[142:143]
	v_cvt_pk_bf16_f32 v142, v166, v167
	v_cvt_pk_bf16_f32 v143, v168, v169
	global_store_dwordx4 v[138:139], v[140:143], off
	v_add_f32_e32 v172, v169, v173
	s_nop 0
	v_pk_mul_f32 v[140:141], v[102:103], v[164:165] op_sel:[0,1]
	s_nop 0
	v_mul_f32_e32 v142, 0x3d372713, v140
	v_mul_f32_e32 v143, 0x3d372713, v141
	v_mul_f32_e32 v142, v140, v142
	v_mul_f32_e32 v143, v141, v143
	v_fma_f32 v142, v140, v142, v140
	v_fma_f32 v143, v141, v143, v141
	v_mul_f32_e32 v142, 0x3fcc422a, v142
	v_mul_f32_e32 v143, 0x3fcc422a, v143
	v_mul_f32_e32 v142, 0xbfb8aa3b, v142
	v_mul_f32_e32 v143, 0xbfb8aa3b, v143
	v_exp_f32_e32 v142, v142
	v_exp_f32_e32 v143, v143
	v_add_f32_e32 v142, 1.0, v142
	v_add_f32_e32 v143, 1.0, v143
	v_rcp_f32_e32 v142, v142
	v_rcp_f32_e32 v143, v143
	s_nop 0
	v_pk_mul_f32 v[140:141], v[140:141], v[142:143]
	v_mul_f32_e32 v142, v169, v169
	v_add_f32_e32 v144, v140, v172
	v_mov_b32_e32 v168, v140
	v_pk_add_f32 v[142:143], v[142:143], v[170:171] op_sel_hi:[0,1]
	v_pk_fma_f32 v[142:143], v[168:169], v[168:169], v[142:143]
	v_add_f32_e32 v168, v141, v144
	v_pk_mul_f32 v[144:145], v[104:105], v[164:165] op_sel:[0,1]
	v_cvt_pk_bf16_f32 v140, v140, v141
	v_mul_f32_e32 v166, 0x3d372713, v144
	v_mul_f32_e32 v167, 0x3d372713, v145
	v_mul_f32_e32 v166, v144, v166
	v_mul_f32_e32 v167, v145, v167
	v_fma_f32 v166, v144, v166, v144
	v_fma_f32 v167, v145, v167, v145
	v_mul_f32_e32 v166, 0x3fcc422a, v166
	v_mul_f32_e32 v167, 0x3fcc422a, v167
	v_mul_f32_e32 v166, 0xbfb8aa3b, v166
	v_mul_f32_e32 v167, 0xbfb8aa3b, v167
	v_exp_f32_e32 v166, v166
	v_exp_f32_e32 v167, v167
	v_add_f32_e32 v166, 1.0, v166
	v_add_f32_e32 v167, 1.0, v167
	v_rcp_f32_e32 v166, v166
	v_rcp_f32_e32 v167, v167
	s_nop 0
	v_pk_mul_f32 v[144:145], v[144:145], v[166:167]
	s_nop 0
	v_add_f32_e32 v169, v144, v168
	v_mul_f32_e32 v168, v141, v141
	v_mov_b32_e32 v166, v144
	v_mov_b32_e32 v167, v141
	v_pk_add_f32 v[142:143], v[168:169], v[142:143] op_sel_hi:[0,1]
	v_pk_fma_f32 v[142:143], v[166:167], v[166:167], v[142:143]
	v_pk_mul_f32 v[166:167], v[98:99], v[164:165] op_sel:[0,1]
	v_add_f32_e32 v170, v145, v169
	v_mul_f32_e32 v168, 0x3d372713, v166
	v_mul_f32_e32 v169, 0x3d372713, v167
	v_mul_f32_e32 v168, v166, v168
	v_mul_f32_e32 v169, v167, v169
	v_fma_f32 v168, v166, v168, v166
	v_fma_f32 v169, v167, v169, v167
	v_mul_f32_e32 v168, 0x3fcc422a, v168
	v_mul_f32_e32 v169, 0x3fcc422a, v169
	v_mul_f32_e32 v168, 0xbfb8aa3b, v168
	v_mul_f32_e32 v169, 0xbfb8aa3b, v169
	v_exp_f32_e32 v168, v168
	v_exp_f32_e32 v169, v169
	v_cvt_pk_bf16_f32 v141, v144, v145
	v_add_f32_e32 v168, 1.0, v168
	v_add_f32_e32 v169, 1.0, v169
	v_rcp_f32_e32 v168, v168
	v_rcp_f32_e32 v169, v169
	s_nop 0
	v_pk_mul_f32 v[166:167], v[166:167], v[168:169]
	s_nop 0
	v_add_f32_e32 v171, v166, v170
	v_mul_f32_e32 v170, v145, v145
	v_mov_b32_e32 v168, v166
	v_mov_b32_e32 v169, v145
	v_pk_add_f32 v[142:143], v[170:171], v[142:143] op_sel_hi:[0,1]
	v_pk_mul_f32 v[144:145], v[100:101], v[164:165] op_sel:[0,1]
	v_pk_fma_f32 v[168:169], v[168:169], v[168:169], v[142:143]
	v_mul_f32_e32 v143, 0x3d372713, v144
	v_mul_f32_e32 v143, v144, v143
	v_fma_f32 v143, v144, v143, v144
	v_mul_f32_e32 v143, 0x3fcc422a, v143
	v_mul_f32_e32 v143, 0xbfb8aa3b, v143
	v_exp_f32_e32 v143, v143
	v_mul_f32_e32 v176, v167, v167
	v_add_f32_e32 v170, v167, v171
	v_cvt_pk_bf16_f32 v142, v166, v167
	v_add_f32_e32 v143, 1.0, v143
	v_rcp_f32_e32 v172, v143
	v_mul_f32_e32 v143, 0x3d372713, v145
	v_mul_f32_e32 v143, v145, v143
	v_fma_f32 v143, v145, v143, v145
	v_mul_f32_e32 v143, 0x3fcc422a, v143
	v_mul_f32_e32 v143, 0xbfb8aa3b, v143
	v_exp_f32_e32 v143, v143
	v_pk_add_f32 v[168:169], v[176:177], v[168:169] op_sel_hi:[0,1]
	v_add_f32_e32 v143, 1.0, v143
	v_rcp_f32_e32 v173, v143
	s_nop 0
	v_pk_mul_f32 v[174:175], v[144:145], v[172:173]
	s_nop 0
	v_mov_b32_e32 v166, v174
	v_mov_b32_e32 v171, v175
	v_pk_fma_f32 v[166:167], v[166:167], v[166:167], v[168:169]
	v_pk_fma_f32 v[144:145], v[144:145], v[172:173], v[170:171]
	v_pk_mul_f32 v[168:169], v[174:175], v[174:175]
	v_pk_mov_b32 v[166:167], v[174:175], v[166:167] op_sel:[1,0]
	v_mov_b32_e32 v145, v169
	v_pk_add_f32 v[144:145], v[144:145], v[166:167]
	v_cvt_pk_bf16_f32 v143, v174, v175
	global_store_dwordx4 v[138:139], v[140:143], off offset:256
	v_mov_b32_e32 v138, v144
	s_nop 1
	v_permlane16_swap_b32_e32 v138, v144
	v_mov_b32_e32 v139, v145
	s_nop 1
	v_permlane16_swap_b32_e32 v139, v145
	s_waitcnt lgkmcnt(0)
	v_pk_add_f32 v[138:139], v[144:145], v[138:139]
	s_nop 0
	v_mov_b32_e32 v140, v138
	s_nop 1
	v_permlane32_swap_b32_e32 v140, v138
	v_mov_b32_e32 v141, v139
	s_nop 1
	v_permlane32_swap_b32_e32 v141, v139
	s_and_saveexec_b64 s[10:11], vcc
	s_cbranch_execz .LBB0_876
	v_lshlrev_b64 v[136:137], 7, v[136:137]
	v_lshl_add_u64 v[136:137], s[0:1], 0, v[136:137]
	s_waitcnt lgkmcnt(0)
	v_pk_add_f32 v[138:139], v[138:139], v[140:141]
	global_store_dwordx2 v[136:137], v[138:139], off
; __device__ __forceinline__ float sigm(float x) { return __builtin_amdgcn_rcpf(1.f + __expf(-x)); }
; __device__ __forceinline__ float gelu_tanh(float x) { return x * sigm(1.5957691216f * (x + 0.044715f * x * x * x)); }
; __device__ __forceinline__ u32x4 pack8(const float* v) { u32x4 w; w.x = cvtpk(v[0], v[1]); w.y = cvtpk(v[2], v[3]); w.z = cvtpk(v[4], v[5]); w.w = cvtpk(v[6], v[7]); return w; }
;     template <int KIND>
;     __device__ __forceinline__ void act_tile(const pg8::f32x4 (&acc)[2][2][4][2], const float (&rs)[2][4], unsigned char* w_, int row0, int colt, int statslot, int fq_) const {
;     ...
;         for (int ai = 0; ai < 2; ++ai)
; #pragma unroll
;             for (int m = 0; m < 4; ++m) {
;                 const int row = row0 + ai * 128 + m * 16;
;                 float s1 = 0.f, s2 = 0.f;
; #pragma unroll
;                 for (int bj = 0; bj < 2; ++bj) {
;                     float v[8];
; #pragma unroll
;                     for (int n = 0; n < 2; ++n)
; #pragma unroll
;                         for (int j = 0; j < 4; ++j) {
;                             const float a = acc[ai][bj][m][n][j] * rs[ai][m];
;                             const float r = KIND == 2 ? sigm(a) : gelu_tanh(a);
;                             v[n * 4 + j] = r;
;                             if (KIND == 1) { s1 += r; s2 += r * r; }
;                         }
;                     *(u32x4*)(base + (size_t)row * ldc + colt + bj * 128) = pack8(v);
;                 }
;                 if (KIND == 1) {
;                     s1 += __shfl_xor(s1, 16); s1 += __shfl_xor(s1, 32); s2 += __shfl_xor(s2, 16); s2 += __shfl_xor(s2, 32);
.LBB0_876:
	s_or_b64 exec, exec, s[10:11]
	s_waitcnt lgkmcnt(0)
	v_pk_mul_f32 v[140:141], v[94:95], v[162:163] op_sel_hi:[1,0]
	v_pk_mul_f32 v[144:145], v[96:97], v[162:163] op_sel_hi:[1,0]
	v_mul_f32_e32 v142, 0x3d372713, v140
	v_mul_f32_e32 v143, 0x3d372713, v141
	v_mul_f32_e32 v142, v140, v142
	v_mul_f32_e32 v143, v141, v143
	v_fma_f32 v142, v140, v142, v140
	v_fma_f32 v143, v141, v143, v141
	v_mul_f32_e32 v166, 0x3d372713, v144
	v_mul_f32_e32 v167, 0x3d372713, v145
	v_mul_f32_e32 v142, 0x3fcc422a, v142
	v_mul_f32_e32 v143, 0x3fcc422a, v143
	v_mul_f32_e32 v166, v144, v166
	v_mul_f32_e32 v167, v145, v167
	v_mul_f32_e32 v142, 0xbfb8aa3b, v142
	v_mul_f32_e32 v143, 0xbfb8aa3b, v143
	v_fma_f32 v166, v144, v166, v144
	v_fma_f32 v167, v145, v167, v145
	v_exp_f32_e32 v142, v142
	v_exp_f32_e32 v143, v143
	v_mul_f32_e32 v166, 0x3fcc422a, v166
	v_mul_f32_e32 v167, 0x3fcc422a, v167
	v_mul_f32_e32 v166, 0xbfb8aa3b, v166
	v_mul_f32_e32 v167, 0xbfb8aa3b, v167
	v_exp_f32_e32 v166, v166
	v_exp_f32_e32 v167, v167
	v_add_f32_e32 v142, 1.0, v142
	v_add_f32_e32 v143, 1.0, v143
	v_rcp_f32_e32 v142, v142
	v_rcp_f32_e32 v143, v143
	v_add_f32_e32 v166, 1.0, v166
	v_add_f32_e32 v167, 1.0, v167
	v_rcp_f32_e32 v166, v166
	v_rcp_f32_e32 v167, v167
	v_pk_mul_f32 v[140:141], v[140:141], v[142:143]
	v_add_u32_e32 v136, 32, v158
	v_add_f32_e32 v142, 0, v140
	v_add_f32_e32 v168, v141, v142
	v_pk_mul_f32 v[144:145], v[144:145], v[166:167]
	v_mul_f32_e32 v142, v141, v141
	v_add_f32_e32 v166, v144, v168
	v_add_f32_e32 v170, v145, v166
	v_pk_mul_f32 v[166:167], v[90:91], v[162:163] op_sel_hi:[1,0]
	v_pk_fma_f32 v[142:143], v[140:141], v[140:141], v[142:143] op_sel_hi:[1,1,0]
	v_mul_f32_e32 v168, 0x3d372713, v166
	v_mul_f32_e32 v169, 0x3d372713, v167
	v_mul_f32_e32 v168, v166, v168
	v_mul_f32_e32 v169, v167, v169
	v_fma_f32 v168, v166, v168, v166
	v_fma_f32 v169, v167, v169, v167
	v_mul_f32_e32 v168, 0x3fcc422a, v168
	v_mul_f32_e32 v169, 0x3fcc422a, v169
	v_mul_f32_e32 v168, 0xbfb8aa3b, v168
	v_mul_f32_e32 v169, 0xbfb8aa3b, v169
	v_exp_f32_e32 v168, v168
	v_exp_f32_e32 v169, v169
	v_pk_fma_f32 v[142:143], v[144:145], v[144:145], v[142:143]
	v_ashrrev_i32_e32 v137, 31, v136
	v_add_f32_e32 v168, 1.0, v168
	v_add_f32_e32 v169, 1.0, v169
	v_rcp_f32_e32 v168, v168
	v_rcp_f32_e32 v169, v169
	v_lshlrev_b64 v[138:139], 11, v[136:137]
	v_lshl_add_u64 v[138:139], v[134:135], 0, v[138:139]
	v_cvt_pk_bf16_f32 v140, v140, v141
	v_pk_mul_f32 v[166:167], v[166:167], v[168:169]
	v_mov_b32_e32 v169, v145
	v_add_f32_e32 v171, v166, v170
	v_mul_f32_e32 v170, v145, v145
	v_mov_b32_e32 v168, v166
	v_pk_add_f32 v[142:143], v[170:171], v[142:143] op_sel_hi:[0,1]
	v_pk_fma_f32 v[142:143], v[168:169], v[168:169], v[142:143]
	v_pk_mul_f32 v[168:169], v[92:93], v[162:163] op_sel_hi:[1,0]
	v_add_f32_e32 v172, v167, v171
	v_mul_f32_e32 v170, 0x3d372713, v168
	v_mul_f32_e32 v171, 0x3d372713, v169
	v_mul_f32_e32 v170, v168, v170
	v_mul_f32_e32 v171, v169, v171
	v_fma_f32 v170, v168, v170, v168
	v_fma_f32 v171, v169, v171, v169
	v_mul_f32_e32 v170, 0x3fcc422a, v170
	v_mul_f32_e32 v171, 0x3fcc422a, v171
	v_mul_f32_e32 v170, 0xbfb8aa3b, v170
	v_mul_f32_e32 v171, 0xbfb8aa3b, v171
	v_exp_f32_e32 v170, v170
	v_exp_f32_e32 v171, v171
	v_cvt_pk_bf16_f32 v141, v144, v145
	v_add_f32_e32 v170, 1.0, v170
	v_add_f32_e32 v171, 1.0, v171
	v_rcp_f32_e32 v170, v170
	v_rcp_f32_e32 v171, v171
	s_nop 0
	v_pk_mul_f32 v[168:169], v[168:169], v[170:171]
	s_nop 0
	v_add_f32_e32 v173, v168, v172
	v_mul_f32_e32 v172, v167, v167
	v_mov_b32_e32 v170, v168
	v_mov_b32_e32 v171, v167
	v_pk_add_f32 v[142:143], v[172:173], v[142:143] op_sel_hi:[0,1]
	v_pk_fma_f32 v[170:171], v[170:171], v[170:171], v[142:143]
	v_cvt_pk_bf16_f32 v142, v166, v167
	v_cvt_pk_bf16_f32 v143, v168, v169
	global_store_dwordx4 v[138:139], v[140:143], off
	v_add_f32_e32 v172, v169, v173
	s_nop 0
	v_pk_mul_f32 v[140:141], v[86:87], v[162:163] op_sel_hi:[1,0]
	s_nop 0
	v_mul_f32_e32 v142, 0x3d372713, v140
	v_mul_f32_e32 v143, 0x3d372713, v141
	v_mul_f32_e32 v142, v140, v142
	v_mul_f32_e32 v143, v141, v143
	v_fma_f32 v142, v140, v142, v140
	v_fma_f32 v143, v141, v143, v141
	v_mul_f32_e32 v142, 0x3fcc422a, v142
	v_mul_f32_e32 v143, 0x3fcc422a, v143
	v_mul_f32_e32 v142, 0xbfb8aa3b, v142
	v_mul_f32_e32 v143, 0xbfb8aa3b, v143
	v_exp_f32_e32 v142, v142
	v_exp_f32_e32 v143, v143
	v_add_f32_e32 v142, 1.0, v142
	v_add_f32_e32 v143, 1.0, v143
	v_rcp_f32_e32 v142, v142
	v_rcp_f32_e32 v143, v143
	s_nop 0
	v_pk_mul_f32 v[140:141], v[140:141], v[142:143]
	v_mul_f32_e32 v142, v169, v169
	v_add_f32_e32 v144, v140, v172
	v_mov_b32_e32 v168, v140
	v_pk_add_f32 v[142:143], v[142:143], v[170:171] op_sel_hi:[0,1]
	v_pk_fma_f32 v[142:143], v[168:169], v[168:169], v[142:143]
	v_add_f32_e32 v168, v141, v144
	v_pk_mul_f32 v[144:145], v[88:89], v[162:163] op_sel_hi:[1,0]
	v_cvt_pk_bf16_f32 v140, v140, v141
	v_mul_f32_e32 v166, 0x3d372713, v144
	v_mul_f32_e32 v167, 0x3d372713, v145
	v_mul_f32_e32 v166, v144, v166
	v_mul_f32_e32 v167, v145, v167
	v_fma_f32 v166, v144, v166, v144
	v_fma_f32 v167, v145, v167, v145
	v_mul_f32_e32 v166, 0x3fcc422a, v166
	v_mul_f32_e32 v167, 0x3fcc422a, v167
	v_mul_f32_e32 v166, 0xbfb8aa3b, v166
	v_mul_f32_e32 v167, 0xbfb8aa3b, v167
	v_exp_f32_e32 v166, v166
	v_exp_f32_e32 v167, v167
	v_add_f32_e32 v166, 1.0, v166
	v_add_f32_e32 v167, 1.0, v167
	v_rcp_f32_e32 v166, v166
	v_rcp_f32_e32 v167, v167
	s_nop 0
	v_pk_mul_f32 v[144:145], v[144:145], v[166:167]
	s_nop 0
	v_add_f32_e32 v169, v144, v168
	v_mul_f32_e32 v168, v141, v141
	v_mov_b32_e32 v166, v144
	v_mov_b32_e32 v167, v141
	v_pk_add_f32 v[142:143], v[168:169], v[142:143] op_sel_hi:[0,1]
; __device__ __forceinline__ float sigm(float x) { return __builtin_amdgcn_rcpf(1.f + __expf(-x)); }
; __device__ __forceinline__ float gelu_tanh(float x) { return x * sigm(1.5957691216f * (x + 0.044715f * x * x * x)); }
; __device__ __forceinline__ u32x4 pack8(const float* v) { u32x4 w; w.x = cvtpk(v[0], v[1]); w.y = cvtpk(v[2], v[3]); w.z = cvtpk(v[4], v[5]); w.w = cvtpk(v[6], v[7]); return w; }
;     template <int KIND>
;     __device__ __forceinline__ void act_tile(const pg8::f32x4 (&acc)[2][2][4][2], const float (&rs)[2][4], unsigned char* w_, int row0, int colt, int statslot, int fq_) const {
;     ...
;         for (int ai = 0; ai < 2; ++ai)
; #pragma unroll
;             for (int m = 0; m < 4; ++m) {
;                 const int row = row0 + ai * 128 + m * 16;
;                 float s1 = 0.f, s2 = 0.f;
; #pragma unroll
;                 for (int bj = 0; bj < 2; ++bj) {
;                     float v[8];
; #pragma unroll
;                     for (int n = 0; n < 2; ++n)
; #pragma unroll
;                         for (int j = 0; j < 4; ++j) {
;                             const float a = acc[ai][bj][m][n][j] * rs[ai][m];
;                             const float r = KIND == 2 ? sigm(a) : gelu_tanh(a);
;                             v[n * 4 + j] = r;
;                             if (KIND == 1) { s1 += r; s2 += r * r; }
;                         }
;                     *(u32x4*)(base + (size_t)row * ldc + colt + bj * 128) = pack8(v);
;                 }
;                 if (KIND == 1) {
;                     s1 += __shfl_xor(s1, 16); s1 += __shfl_xor(s1, 32); s2 += __shfl_xor(s2, 16); s2 += __shfl_xor(s2, 32);
;                     if (fq_ == 0) { float* sp = (float*)(w_ + WS_VSTAT) + ((size_t)row * 16 + statslot) * 2; sp[0] = s1; sp[1] = s2; }
;                 }
	v_pk_fma_f32 v[142:143], v[166:167], v[166:167], v[142:143]
	v_pk_mul_f32 v[166:167], v[82:83], v[162:163] op_sel_hi:[1,0]
	v_add_f32_e32 v170, v145, v169
	v_mul_f32_e32 v168, 0x3d372713, v166
	v_mul_f32_e32 v169, 0x3d372713, v167
	v_mul_f32_e32 v168, v166, v168
	v_mul_f32_e32 v169, v167, v169
	v_fma_f32 v168, v166, v168, v166
	v_fma_f32 v169, v167, v169, v167
	v_mul_f32_e32 v168, 0x3fcc422a, v168
	v_mul_f32_e32 v169, 0x3fcc422a, v169
	v_mul_f32_e32 v168, 0xbfb8aa3b, v168
	v_mul_f32_e32 v169, 0xbfb8aa3b, v169
	v_exp_f32_e32 v168, v168
	v_exp_f32_e32 v169, v169
	v_cvt_pk_bf16_f32 v141, v144, v145
	v_add_f32_e32 v168, 1.0, v168
	v_add_f32_e32 v169, 1.0, v169
	v_rcp_f32_e32 v168, v168
	v_rcp_f32_e32 v169, v169
	s_nop 0
	v_pk_mul_f32 v[166:167], v[166:167], v[168:169]
	s_nop 0
	v_add_f32_e32 v171, v166, v170
	v_mul_f32_e32 v170, v145, v145
	v_mov_b32_e32 v168, v166
	v_mov_b32_e32 v169, v145
	v_pk_add_f32 v[142:143], v[170:171], v[142:143] op_sel_hi:[0,1]
	v_pk_mul_f32 v[144:145], v[84:85], v[162:163] op_sel_hi:[1,0]
	v_pk_fma_f32 v[168:169], v[168:169], v[168:169], v[142:143]
	v_mul_f32_e32 v143, 0x3d372713, v144
	v_mul_f32_e32 v143, v144, v143
	v_fma_f32 v143, v144, v143, v144
	v_mul_f32_e32 v143, 0x3fcc422a, v143
	v_mul_f32_e32 v143, 0xbfb8aa3b, v143
	v_exp_f32_e32 v143, v143
	v_mul_f32_e32 v176, v167, v167
	v_add_f32_e32 v170, v167, v171
	v_cvt_pk_bf16_f32 v142, v166, v167
	v_add_f32_e32 v143, 1.0, v143
	v_rcp_f32_e32 v172, v143
	v_mul_f32_e32 v143, 0x3d372713, v145
	v_mul_f32_e32 v143, v145, v143
	v_fma_f32 v143, v145, v143, v145
	v_mul_f32_e32 v143, 0x3fcc422a, v143
	v_mul_f32_e32 v143, 0xbfb8aa3b, v143
	v_exp_f32_e32 v143, v143
	v_pk_add_f32 v[168:169], v[176:177], v[168:169] op_sel_hi:[0,1]
	v_add_f32_e32 v143, 1.0, v143
	v_rcp_f32_e32 v173, v143
	s_nop 0
	v_pk_mul_f32 v[174:175], v[144:145], v[172:173]
	s_nop 0
	v_mov_b32_e32 v166, v174
	v_mov_b32_e32 v171, v175
	v_pk_fma_f32 v[166:167], v[166:167], v[166:167], v[168:169]
	v_pk_fma_f32 v[144:145], v[144:145], v[172:173], v[170:171]
	v_pk_mul_f32 v[168:169], v[174:175], v[174:175]
	v_pk_mov_b32 v[166:167], v[174:175], v[166:167] op_sel:[1,0]
	v_mov_b32_e32 v145, v169
	v_pk_add_f32 v[144:145], v[144:145], v[166:167]
	v_cvt_pk_bf16_f32 v143, v174, v175
	global_store_dwordx4 v[138:139], v[140:143], off offset:256
	v_mov_b32_e32 v138, v144
	s_nop 1
	v_permlane16_swap_b32_e32 v138, v144
	v_mov_b32_e32 v139, v145
	s_nop 1
	v_permlane16_swap_b32_e32 v139, v145
	s_waitcnt lgkmcnt(0)
	v_pk_add_f32 v[138:139], v[144:145], v[138:139]
	s_nop 0
	v_mov_b32_e32 v140, v138
	s_nop 1
	v_permlane32_swap_b32_e32 v140, v138
	v_mov_b32_e32 v141, v139
	s_nop 1
	v_permlane32_swap_b32_e32 v141, v139
	s_and_saveexec_b64 s[10:11], vcc
	s_movk_i32 s38, 0x6000
	s_cbranch_execz .LBB0_878
	v_lshlrev_b64 v[136:137], 7, v[136:137]
	v_lshl_add_u64 v[136:137], s[0:1], 0, v[136:137]
	s_waitcnt lgkmcnt(0)
	v_pk_add_f32 v[138:139], v[138:139], v[140:141]
	global_store_dwordx2 v[136:137], v[138:139], off
.LBB0_878:
	s_or_b64 exec, exec, s[10:11]
	s_waitcnt lgkmcnt(0)
	v_pk_mul_f32 v[140:141], v[78:79], v[162:163] op_sel:[0,1]
	v_pk_mul_f32 v[144:145], v[80:81], v[162:163] op_sel:[0,1]
	v_mul_f32_e32 v142, 0x3d372713, v140
	v_mul_f32_e32 v143, 0x3d372713, v141
	v_mul_f32_e32 v142, v140, v142
	v_mul_f32_e32 v143, v141, v143
	v_fma_f32 v142, v140, v142, v140
	v_fma_f32 v143, v141, v143, v141
	v_mul_f32_e32 v166, 0x3d372713, v144
	v_mul_f32_e32 v167, 0x3d372713, v145
	v_mul_f32_e32 v142, 0x3fcc422a, v142
	v_mul_f32_e32 v143, 0x3fcc422a, v143
	v_mul_f32_e32 v166, v144, v166
	v_mul_f32_e32 v167, v145, v167
	v_mul_f32_e32 v142, 0xbfb8aa3b, v142
	v_mul_f32_e32 v143, 0xbfb8aa3b, v143
	v_fma_f32 v166, v144, v166, v144
	v_fma_f32 v167, v145, v167, v145
	v_exp_f32_e32 v142, v142
	v_exp_f32_e32 v143, v143
	v_mul_f32_e32 v166, 0x3fcc422a, v166
	v_mul_f32_e32 v167, 0x3fcc422a, v167
	v_mul_f32_e32 v166, 0xbfb8aa3b, v166
	v_mul_f32_e32 v167, 0xbfb8aa3b, v167
	v_exp_f32_e32 v166, v166
	v_exp_f32_e32 v167, v167
	v_add_f32_e32 v142, 1.0, v142
	v_add_f32_e32 v143, 1.0, v143
	v_rcp_f32_e32 v142, v142
	v_rcp_f32_e32 v143, v143
	v_add_f32_e32 v166, 1.0, v166
	v_add_f32_e32 v167, 1.0, v167
	v_rcp_f32_e32 v166, v166
	v_rcp_f32_e32 v167, v167
	v_pk_mul_f32 v[140:141], v[140:141], v[142:143]
	v_add_u32_e32 v136, 48, v158
	v_add_f32_e32 v142, 0, v140
	v_add_f32_e32 v168, v141, v142
	v_pk_mul_f32 v[144:145], v[144:145], v[166:167]
	v_mul_f32_e32 v142, v141, v141
	v_add_f32_e32 v166, v144, v168
	v_add_f32_e32 v170, v145, v166
	v_pk_mul_f32 v[166:167], v[74:75], v[162:163] op_sel:[0,1]
	v_pk_fma_f32 v[142:143], v[140:141], v[140:141], v[142:143] op_sel_hi:[1,1,0]
	v_mul_f32_e32 v168, 0x3d372713, v166
	v_mul_f32_e32 v169, 0x3d372713, v167
	v_mul_f32_e32 v168, v166, v168
	v_mul_f32_e32 v169, v167, v169
	v_fma_f32 v168, v166, v168, v166
	v_fma_f32 v169, v167, v169, v167
	v_mul_f32_e32 v168, 0x3fcc422a, v168
	v_mul_f32_e32 v169, 0x3fcc422a, v169
	v_mul_f32_e32 v168, 0xbfb8aa3b, v168
	v_mul_f32_e32 v169, 0xbfb8aa3b, v169
	v_exp_f32_e32 v168, v168
	v_exp_f32_e32 v169, v169
	v_pk_fma_f32 v[142:143], v[144:145], v[144:145], v[142:143]
	v_ashrrev_i32_e32 v137, 31, v136
	v_add_f32_e32 v168, 1.0, v168
	v_add_f32_e32 v169, 1.0, v169
	v_rcp_f32_e32 v168, v168
	v_rcp_f32_e32 v169, v169
	v_lshlrev_b64 v[138:139], 11, v[136:137]
	v_lshl_add_u64 v[138:139], v[134:135], 0, v[138:139]
	v_cvt_pk_bf16_f32 v140, v140, v141
	v_pk_mul_f32 v[166:167], v[166:167], v[168:169]
	v_mov_b32_e32 v169, v145
	v_add_f32_e32 v171, v166, v170
	v_mul_f32_e32 v170, v145, v145
	v_mov_b32_e32 v168, v166
	v_pk_add_f32 v[142:143], v[170:171], v[142:143] op_sel_hi:[0,1]
; __device__ __forceinline__ float sigm(float x) { return __builtin_amdgcn_rcpf(1.f + __expf(-x)); }
; __device__ __forceinline__ float gelu_tanh(float x) { return x * sigm(1.5957691216f * (x + 0.044715f * x * x * x)); }
; __device__ __forceinline__ u32x4 pack8(const float* v) { u32x4 w; w.x = cvtpk(v[0], v[1]); w.y = cvtpk(v[2], v[3]); w.z = cvtpk(v[4], v[5]); w.w = cvtpk(v[6], v[7]); return w; }
;     template <int KIND>
;     __device__ __forceinline__ void act_tile(const pg8::f32x4 (&acc)[2][2][4][2], const float (&rs)[2][4], unsigned char* w_, int row0, int colt, int statslot, int fq_) const {
;     ...
;         for (int ai = 0; ai < 2; ++ai)
; #pragma unroll
;             for (int m = 0; m < 4; ++m) {
;                 const int row = row0 + ai * 128 + m * 16;
;                 float s1 = 0.f, s2 = 0.f;
; #pragma unroll
;                 for (int bj = 0; bj < 2; ++bj) {
;                     float v[8];
; #pragma unroll
;                     for (int n = 0; n < 2; ++n)
; #pragma unroll
;                         for (int j = 0; j < 4; ++j) {
;                             const float a = acc[ai][bj][m][n][j] * rs[ai][m];
;                             const float r = KIND == 2 ? sigm(a) : gelu_tanh(a);
;                             v[n * 4 + j] = r;
;                             if (KIND == 1) { s1 += r; s2 += r * r; }
;                         }
;                     *(u32x4*)(base + (size_t)row * ldc + colt + bj * 128) = pack8(v);
;                 }
;                 if (KIND == 1) {
;                     s1 += __shfl_xor(s1, 16); s1 += __shfl_xor(s1, 32); s2 += __shfl_xor(s2, 16); s2 += __shfl_xor(s2, 32);
;                     if (fq_ == 0) { float* sp = (float*)(w_ + WS_VSTAT) + ((size_t)row * 16 + statslot) * 2; sp[0] = s1; sp[1] = s2; }
;                 }
	v_pk_fma_f32 v[142:143], v[168:169], v[168:169], v[142:143]
	v_pk_mul_f32 v[168:169], v[76:77], v[162:163] op_sel:[0,1]
	v_add_f32_e32 v172, v167, v171
	v_mul_f32_e32 v170, 0x3d372713, v168
	v_mul_f32_e32 v171, 0x3d372713, v169
	v_mul_f32_e32 v170, v168, v170
	v_mul_f32_e32 v171, v169, v171
	v_fma_f32 v170, v168, v170, v168
	v_fma_f32 v171, v169, v171, v169
	v_mul_f32_e32 v170, 0x3fcc422a, v170
	v_mul_f32_e32 v171, 0x3fcc422a, v171
	v_mul_f32_e32 v170, 0xbfb8aa3b, v170
	v_mul_f32_e32 v171, 0xbfb8aa3b, v171
	v_exp_f32_e32 v170, v170
	v_exp_f32_e32 v171, v171
	v_cvt_pk_bf16_f32 v141, v144, v145
	v_add_f32_e32 v170, 1.0, v170
	v_add_f32_e32 v171, 1.0, v171
	v_rcp_f32_e32 v170, v170
	v_rcp_f32_e32 v171, v171
	s_nop 0
	v_pk_mul_f32 v[168:169], v[168:169], v[170:171]
	s_nop 0
	v_add_f32_e32 v173, v168, v172
	v_mul_f32_e32 v172, v167, v167
	v_mov_b32_e32 v170, v168
	v_mov_b32_e32 v171, v167
	v_pk_add_f32 v[142:143], v[172:173], v[142:143] op_sel_hi:[0,1]
	v_pk_fma_f32 v[170:171], v[170:171], v[170:171], v[142:143]
	v_cvt_pk_bf16_f32 v142, v166, v167
	v_cvt_pk_bf16_f32 v143, v168, v169
	global_store_dwordx4 v[138:139], v[140:143], off
	v_add_f32_e32 v172, v169, v173
	s_nop 0
	v_pk_mul_f32 v[140:141], v[70:71], v[162:163] op_sel:[0,1]
	s_nop 0
	v_mul_f32_e32 v142, 0x3d372713, v140
	v_mul_f32_e32 v143, 0x3d372713, v141
	v_mul_f32_e32 v142, v140, v142
	v_mul_f32_e32 v143, v141, v143
	v_fma_f32 v142, v140, v142, v140
	v_fma_f32 v143, v141, v143, v141
	v_mul_f32_e32 v142, 0x3fcc422a, v142
	v_mul_f32_e32 v143, 0x3fcc422a, v143
	v_mul_f32_e32 v142, 0xbfb8aa3b, v142
	v_mul_f32_e32 v143, 0xbfb8aa3b, v143
	v_exp_f32_e32 v142, v142
	v_exp_f32_e32 v143, v143
	v_add_f32_e32 v142, 1.0, v142
	v_add_f32_e32 v143, 1.0, v143
	v_rcp_f32_e32 v142, v142
	v_rcp_f32_e32 v143, v143
	s_nop 0
	v_pk_mul_f32 v[140:141], v[140:141], v[142:143]
	v_mul_f32_e32 v142, v169, v169
	v_add_f32_e32 v144, v140, v172
	v_mov_b32_e32 v168, v140
	v_pk_add_f32 v[142:143], v[142:143], v[170:171] op_sel_hi:[0,1]
	v_pk_fma_f32 v[142:143], v[168:169], v[168:169], v[142:143]
	v_add_f32_e32 v168, v141, v144
	v_pk_mul_f32 v[144:145], v[72:73], v[162:163] op_sel:[0,1]
	v_cvt_pk_bf16_f32 v140, v140, v141
	v_mul_f32_e32 v166, 0x3d372713, v144
	v_mul_f32_e32 v167, 0x3d372713, v145
	v_mul_f32_e32 v166, v144, v166
	v_mul_f32_e32 v167, v145, v167
	v_fma_f32 v166, v144, v166, v144
	v_fma_f32 v167, v145, v167, v145
	v_mul_f32_e32 v166, 0x3fcc422a, v166
	v_mul_f32_e32 v167, 0x3fcc422a, v167
	v_mul_f32_e32 v166, 0xbfb8aa3b, v166
	v_mul_f32_e32 v167, 0xbfb8aa3b, v167
	v_exp_f32_e32 v166, v166
	v_exp_f32_e32 v167, v167
	v_add_f32_e32 v166, 1.0, v166
	v_add_f32_e32 v167, 1.0, v167
	v_rcp_f32_e32 v166, v166
	v_rcp_f32_e32 v167, v167
	s_nop 0
	v_pk_mul_f32 v[144:145], v[144:145], v[166:167]
	s_nop 0
	v_add_f32_e32 v169, v144, v168
	v_mul_f32_e32 v168, v141, v141
	v_mov_b32_e32 v166, v144
	v_mov_b32_e32 v167, v141
	v_pk_add_f32 v[142:143], v[168:169], v[142:143] op_sel_hi:[0,1]
	v_pk_fma_f32 v[142:143], v[166:167], v[166:167], v[142:143]
	v_pk_mul_f32 v[166:167], v[66:67], v[162:163] op_sel:[0,1]
	v_add_f32_e32 v170, v145, v169
	v_mul_f32_e32 v168, 0x3d372713, v166
	v_mul_f32_e32 v169, 0x3d372713, v167
	v_mul_f32_e32 v168, v166, v168
	v_mul_f32_e32 v169, v167, v169
	v_fma_f32 v168, v166, v168, v166
	v_fma_f32 v169, v167, v169, v167
	v_mul_f32_e32 v168, 0x3fcc422a, v168
	v_mul_f32_e32 v169, 0x3fcc422a, v169
	v_mul_f32_e32 v168, 0xbfb8aa3b, v168
	v_mul_f32_e32 v169, 0xbfb8aa3b, v169
	v_exp_f32_e32 v168, v168
	v_exp_f32_e32 v169, v169
	v_cvt_pk_bf16_f32 v141, v144, v145
	v_add_f32_e32 v168, 1.0, v168
	v_add_f32_e32 v169, 1.0, v169
	v_rcp_f32_e32 v168, v168
	v_rcp_f32_e32 v169, v169
	s_nop 0
	v_pk_mul_f32 v[166:167], v[166:167], v[168:169]
	s_nop 0
	v_add_f32_e32 v171, v166, v170
	v_mul_f32_e32 v170, v145, v145
	v_mov_b32_e32 v168, v166
	v_mov_b32_e32 v169, v145
	v_pk_add_f32 v[142:143], v[170:171], v[142:143] op_sel_hi:[0,1]
	v_pk_mul_f32 v[144:145], v[68:69], v[162:163] op_sel:[0,1]
	v_pk_fma_f32 v[168:169], v[168:169], v[168:169], v[142:143]
	v_mul_f32_e32 v143, 0x3d372713, v144
	v_mul_f32_e32 v143, v144, v143
	v_fma_f32 v143, v144, v143, v144
	v_mul_f32_e32 v143, 0x3fcc422a, v143
	v_mul_f32_e32 v143, 0xbfb8aa3b, v143
	v_exp_f32_e32 v143, v143
	v_mul_f32_e32 v176, v167, v167
	v_add_f32_e32 v170, v167, v171
	v_cvt_pk_bf16_f32 v142, v166, v167
	v_add_f32_e32 v143, 1.0, v143
	v_rcp_f32_e32 v172, v143
	v_mul_f32_e32 v143, 0x3d372713, v145
	v_mul_f32_e32 v143, v145, v143
	v_fma_f32 v143, v145, v143, v145
	v_mul_f32_e32 v143, 0x3fcc422a, v143
	v_mul_f32_e32 v143, 0xbfb8aa3b, v143
	v_exp_f32_e32 v143, v143
	v_pk_add_f32 v[168:169], v[176:177], v[168:169] op_sel_hi:[0,1]
	v_add_f32_e32 v143, 1.0, v143
	v_rcp_f32_e32 v173, v143
	s_nop 0
	v_pk_mul_f32 v[174:175], v[144:145], v[172:173]
	s_nop 0
	v_mov_b32_e32 v166, v174
	v_mov_b32_e32 v171, v175
	v_pk_fma_f32 v[166:167], v[166:167], v[166:167], v[168:169]
	v_pk_fma_f32 v[144:145], v[144:145], v[172:173], v[170:171]
	v_pk_mul_f32 v[168:169], v[174:175], v[174:175]
	v_pk_mov_b32 v[166:167], v[174:175], v[166:167] op_sel:[1,0]
	v_mov_b32_e32 v145, v169
	v_pk_add_f32 v[144:145], v[144:145], v[166:167]
	v_cvt_pk_bf16_f32 v143, v174, v175
	global_store_dwordx4 v[138:139], v[140:143], off offset:256
	v_mov_b32_e32 v138, v144
	s_nop 1
	v_permlane16_swap_b32_e32 v138, v144
	v_mov_b32_e32 v139, v145
	s_nop 1
	v_permlane16_swap_b32_e32 v139, v145
	s_waitcnt lgkmcnt(0)
	v_pk_add_f32 v[138:139], v[144:145], v[138:139]
	s_nop 0
	v_mov_b32_e32 v140, v138
	s_nop 1
	v_permlane32_swap_b32_e32 v140, v138
	v_mov_b32_e32 v141, v139
	s_nop 1
	v_permlane32_swap_b32_e32 v141, v139
	s_and_saveexec_b64 s[10:11], vcc
	s_cbranch_execz .LBB0_880
	v_lshlrev_b64 v[136:137], 7, v[136:137]
	v_lshl_add_u64 v[136:137], s[0:1], 0, v[136:137]
	s_waitcnt lgkmcnt(0)
	v_pk_add_f32 v[138:139], v[138:139], v[140:141]
	global_store_dwordx2 v[136:137], v[138:139], off
; __device__ __forceinline__ u32x4 pack8(const float* v) { u32x4 w; w.x = cvtpk(v[0], v[1]); w.y = cvtpk(v[2], v[3]); w.z = cvtpk(v[4], v[5]); w.w = cvtpk(v[6], v[7]); return w; }
; __device__ __forceinline__ float sigm(float x) { return __builtin_amdgcn_rcpf(1.f + __expf(-x)); }
; __device__ __forceinline__ float siluf_(float x) { return x * sigm(x); }
; __device__ __forceinline__ float gelu_tanh(float x) { return x * sigm(1.5957691216f * (x + 0.044715f * x * x * x)); }
;     template <int KIND>
;     __device__ __forceinline__ void act_tile(const pg8::f32x4 (&acc)[2][2][4][2], const float (&rs)[2][4], unsigned char* w_, int row0, int colt, int statslot, int fq_) const {
;     ...
; #pragma unroll
;         for (int ai = 0; ai < 2; ++ai)
; #pragma unroll
;             for (int m = 0; m < 4; ++m) {
;                 const int row = row0 + ai * 128 + m * 16;
;                 float s1 = 0.f, s2 = 0.f;
; #pragma unroll
;                 for (int bj = 0; bj < 2; ++bj) {
;                     float v[8];
; #pragma unroll
;                     for (int n = 0; n < 2; ++n)
; #pragma unroll
;                         for (int j = 0; j < 4; ++j) {
;                             const float a = acc[ai][bj][m][n][j] * rs[ai][m];
;                             const float r = KIND == 2 ? sigm(a) : gelu_tanh(a);
;                             v[n * 4 + j] = r;
;                             if (KIND == 1) { s1 += r; s2 += r * r; }
;                         }
;                     *(u32x4*)(base + (size_t)row * ldc + colt + bj * 128) = pack8(v);
.LBB0_880:
	s_or_b64 exec, exec, s[10:11]
	s_waitcnt lgkmcnt(0)
	v_pk_mul_f32 v[140:141], v[62:63], v[160:161] op_sel_hi:[1,0]
	v_pk_mul_f32 v[144:145], v[64:65], v[160:161] op_sel_hi:[1,0]
	v_mul_f32_e32 v142, 0x3d372713, v140
	v_mul_f32_e32 v143, 0x3d372713, v141
	v_mul_f32_e32 v142, v140, v142
	v_mul_f32_e32 v143, v141, v143
	v_fma_f32 v142, v140, v142, v140
	v_fma_f32 v143, v141, v143, v141
	v_mul_f32_e32 v166, 0x3d372713, v144
	v_mul_f32_e32 v167, 0x3d372713, v145
	v_mul_f32_e32 v142, 0x3fcc422a, v142
	v_mul_f32_e32 v143, 0x3fcc422a, v143
	v_mul_f32_e32 v166, v144, v166
	v_mul_f32_e32 v167, v145, v167
	v_mul_f32_e32 v142, 0xbfb8aa3b, v142
	v_mul_f32_e32 v143, 0xbfb8aa3b, v143
	v_fma_f32 v166, v144, v166, v144
	v_fma_f32 v167, v145, v167, v145
	v_exp_f32_e32 v142, v142
	v_exp_f32_e32 v143, v143
	v_mul_f32_e32 v166, 0x3fcc422a, v166
	v_mul_f32_e32 v167, 0x3fcc422a, v167
	v_mul_f32_e32 v166, 0xbfb8aa3b, v166
	v_mul_f32_e32 v167, 0xbfb8aa3b, v167
	v_exp_f32_e32 v166, v166
	v_exp_f32_e32 v167, v167
	v_add_f32_e32 v142, 1.0, v142
	v_add_f32_e32 v143, 1.0, v143
	v_rcp_f32_e32 v142, v142
	v_rcp_f32_e32 v143, v143
	v_add_f32_e32 v166, 1.0, v166
	v_add_f32_e32 v167, 1.0, v167
	v_rcp_f32_e32 v166, v166
	v_rcp_f32_e32 v167, v167
	v_pk_mul_f32 v[140:141], v[140:141], v[142:143]
	v_add_u32_e32 v136, 0x80, v158
	v_add_f32_e32 v142, 0, v140
	v_add_f32_e32 v168, v141, v142
	v_pk_mul_f32 v[144:145], v[144:145], v[166:167]
	v_mul_f32_e32 v142, v141, v141
	v_add_f32_e32 v166, v144, v168
	v_add_f32_e32 v170, v145, v166
	v_pk_mul_f32 v[166:167], v[58:59], v[160:161] op_sel_hi:[1,0]
	v_pk_fma_f32 v[142:143], v[140:141], v[140:141], v[142:143] op_sel_hi:[1,1,0]
	v_mul_f32_e32 v168, 0x3d372713, v166
	v_mul_f32_e32 v169, 0x3d372713, v167
	v_mul_f32_e32 v168, v166, v168
	v_mul_f32_e32 v169, v167, v169
	v_fma_f32 v168, v166, v168, v166
	v_fma_f32 v169, v167, v169, v167
	v_mul_f32_e32 v168, 0x3fcc422a, v168
	v_mul_f32_e32 v169, 0x3fcc422a, v169
	v_mul_f32_e32 v168, 0xbfb8aa3b, v168
	v_mul_f32_e32 v169, 0xbfb8aa3b, v169
	v_exp_f32_e32 v168, v168
	v_exp_f32_e32 v169, v169
	v_pk_fma_f32 v[142:143], v[144:145], v[144:145], v[142:143]
	v_ashrrev_i32_e32 v137, 31, v136
	v_add_f32_e32 v168, 1.0, v168
	v_add_f32_e32 v169, 1.0, v169
	v_rcp_f32_e32 v168, v168
	v_rcp_f32_e32 v169, v169
	v_lshlrev_b64 v[138:139], 11, v[136:137]
	v_lshl_add_u64 v[138:139], v[134:135], 0, v[138:139]
	v_cvt_pk_bf16_f32 v140, v140, v141
	v_pk_mul_f32 v[166:167], v[166:167], v[168:169]
	v_mov_b32_e32 v169, v145
	v_add_f32_e32 v171, v166, v170
	v_mul_f32_e32 v170, v145, v145
	v_mov_b32_e32 v168, v166
	v_pk_add_f32 v[142:143], v[170:171], v[142:143] op_sel_hi:[0,1]
	v_pk_fma_f32 v[142:143], v[168:169], v[168:169], v[142:143]
	v_pk_mul_f32 v[168:169], v[60:61], v[160:161] op_sel_hi:[1,0]
	v_add_f32_e32 v172, v167, v171
	v_mul_f32_e32 v170, 0x3d372713, v168
	v_mul_f32_e32 v171, 0x3d372713, v169
	v_mul_f32_e32 v170, v168, v170
	v_mul_f32_e32 v171, v169, v171
	v_fma_f32 v170, v168, v170, v168
	v_fma_f32 v171, v169, v171, v169
	v_mul_f32_e32 v170, 0x3fcc422a, v170
	v_mul_f32_e32 v171, 0x3fcc422a, v171
	v_mul_f32_e32 v170, 0xbfb8aa3b, v170
	v_mul_f32_e32 v171, 0xbfb8aa3b, v171
	v_exp_f32_e32 v170, v170
	v_exp_f32_e32 v171, v171
	v_cvt_pk_bf16_f32 v141, v144, v145
	v_add_f32_e32 v170, 1.0, v170
	v_add_f32_e32 v171, 1.0, v171
	v_rcp_f32_e32 v170, v170
	v_rcp_f32_e32 v171, v171
	s_nop 0
	v_pk_mul_f32 v[168:169], v[168:169], v[170:171]
	s_nop 0
	v_add_f32_e32 v173, v168, v172
	v_mul_f32_e32 v172, v167, v167
	v_mov_b32_e32 v170, v168
	v_mov_b32_e32 v171, v167
	v_pk_add_f32 v[142:143], v[172:173], v[142:143] op_sel_hi:[0,1]
	v_pk_fma_f32 v[170:171], v[170:171], v[170:171], v[142:143]
	v_cvt_pk_bf16_f32 v142, v166, v167
	v_cvt_pk_bf16_f32 v143, v168, v169
	global_store_dwordx4 v[138:139], v[140:143], off
	v_add_f32_e32 v172, v169, v173
	s_nop 0
	v_pk_mul_f32 v[140:141], v[54:55], v[160:161] op_sel_hi:[1,0]
	s_nop 0
	v_mul_f32_e32 v142, 0x3d372713, v140
	v_mul_f32_e32 v143, 0x3d372713, v141
	v_mul_f32_e32 v142, v140, v142
	v_mul_f32_e32 v143, v141, v143
	v_fma_f32 v142, v140, v142, v140
	v_fma_f32 v143, v141, v143, v141
	v_mul_f32_e32 v142, 0x3fcc422a, v142
	v_mul_f32_e32 v143, 0x3fcc422a, v143
	v_mul_f32_e32 v142, 0xbfb8aa3b, v142
	v_mul_f32_e32 v143, 0xbfb8aa3b, v143
	v_exp_f32_e32 v142, v142
	v_exp_f32_e32 v143, v143
	v_add_f32_e32 v142, 1.0, v142
	v_add_f32_e32 v143, 1.0, v143
	v_rcp_f32_e32 v142, v142
	v_rcp_f32_e32 v143, v143
	s_nop 0
	v_pk_mul_f32 v[140:141], v[140:141], v[142:143]
	v_mul_f32_e32 v142, v169, v169
	v_add_f32_e32 v144, v140, v172
	v_mov_b32_e32 v168, v140
	v_pk_add_f32 v[142:143], v[142:143], v[170:171] op_sel_hi:[0,1]
	v_pk_fma_f32 v[142:143], v[168:169], v[168:169], v[142:143]
	v_add_f32_e32 v168, v141, v144
	v_pk_mul_f32 v[144:145], v[56:57], v[160:161] op_sel_hi:[1,0]
	v_cvt_pk_bf16_f32 v140, v140, v141
	v_mul_f32_e32 v166, 0x3d372713, v144
	v_mul_f32_e32 v167, 0x3d372713, v145
	v_mul_f32_e32 v166, v144, v166
	v_mul_f32_e32 v167, v145, v167
	v_fma_f32 v166, v144, v166, v144
	v_fma_f32 v167, v145, v167, v145
	v_mul_f32_e32 v166, 0x3fcc422a, v166
	v_mul_f32_e32 v167, 0x3fcc422a, v167
	v_mul_f32_e32 v166, 0xbfb8aa3b, v166
	v_mul_f32_e32 v167, 0xbfb8aa3b, v167
	v_exp_f32_e32 v166, v166
	v_exp_f32_e32 v167, v167
	v_add_f32_e32 v166, 1.0, v166
	v_add_f32_e32 v167, 1.0, v167
	v_rcp_f32_e32 v166, v166
	v_rcp_f32_e32 v167, v167
	s_nop 0
	v_pk_mul_f32 v[144:145], v[144:145], v[166:167]
	s_nop 0
	v_add_f32_e32 v169, v144, v168
	v_mul_f32_e32 v168, v141, v141
	v_mov_b32_e32 v166, v144
	v_mov_b32_e32 v167, v141
	v_pk_add_f32 v[142:143], v[168:169], v[142:143] op_sel_hi:[0,1]
; __device__ __forceinline__ u32x4 pack8(const float* v) { u32x4 w; w.x = cvtpk(v[0], v[1]); w.y = cvtpk(v[2], v[3]); w.z = cvtpk(v[4], v[5]); w.w = cvtpk(v[6], v[7]); return w; }
; __device__ __forceinline__ float sigm(float x) { return __builtin_amdgcn_rcpf(1.f + __expf(-x)); }
; __device__ __forceinline__ float siluf_(float x) { return x * sigm(x); }
; __device__ __forceinline__ float gelu_tanh(float x) { return x * sigm(1.5957691216f * (x + 0.044715f * x * x * x)); }
;     template <int KIND>
;     __device__ __forceinline__ void act_tile(const pg8::f32x4 (&acc)[2][2][4][2], const float (&rs)[2][4], unsigned char* w_, int row0, int colt, int statslot, int fq_) const {
;     ...
;                 for (int bj = 0; bj < 2; ++bj) {
;                     float v[8];
; #pragma unroll
;                     for (int n = 0; n < 2; ++n)
; #pragma unroll
;                         for (int j = 0; j < 4; ++j) {
;                             const float a = acc[ai][bj][m][n][j] * rs[ai][m];
;                             const float r = KIND == 2 ? sigm(a) : gelu_tanh(a);
;                             v[n * 4 + j] = r;
;                             if (KIND == 1) { s1 += r; s2 += r * r; }
;                         }
;                     *(u32x4*)(base + (size_t)row * ldc + colt + bj * 128) = pack8(v);
;                 }
;                 if (KIND == 1) {
;                     s1 += __shfl_xor(s1, 16); s1 += __shfl_xor(s1, 32); s2 += __shfl_xor(s2, 16); s2 += __shfl_xor(s2, 32);
;                     if (fq_ == 0) { float* sp = (float*)(w_ + WS_VSTAT) + ((size_t)row * 16 + statslot) * 2; sp[0] = s1; sp[1] = s2; }
;                 }
	v_pk_fma_f32 v[142:143], v[166:167], v[166:167], v[142:143]
	v_pk_mul_f32 v[166:167], v[50:51], v[160:161] op_sel_hi:[1,0]
	v_add_f32_e32 v170, v145, v169
	v_mul_f32_e32 v168, 0x3d372713, v166
	v_mul_f32_e32 v169, 0x3d372713, v167
	v_mul_f32_e32 v168, v166, v168
	v_mul_f32_e32 v169, v167, v169
	v_fma_f32 v168, v166, v168, v166
	v_fma_f32 v169, v167, v169, v167
	v_mul_f32_e32 v168, 0x3fcc422a, v168
	v_mul_f32_e32 v169, 0x3fcc422a, v169
	v_mul_f32_e32 v168, 0xbfb8aa3b, v168
	v_mul_f32_e32 v169, 0xbfb8aa3b, v169
	v_exp_f32_e32 v168, v168
	v_exp_f32_e32 v169, v169
	v_cvt_pk_bf16_f32 v141, v144, v145
	v_add_f32_e32 v168, 1.0, v168
	v_add_f32_e32 v169, 1.0, v169
	v_rcp_f32_e32 v168, v168
	v_rcp_f32_e32 v169, v169
	s_nop 0
	v_pk_mul_f32 v[166:167], v[166:167], v[168:169]
	s_nop 0
	v_add_f32_e32 v171, v166, v170
	v_mul_f32_e32 v170, v145, v145
	v_mov_b32_e32 v168, v166
	v_mov_b32_e32 v169, v145
	v_pk_add_f32 v[142:143], v[170:171], v[142:143] op_sel_hi:[0,1]
	v_pk_mul_f32 v[144:145], v[52:53], v[160:161] op_sel_hi:[1,0]
	v_pk_fma_f32 v[168:169], v[168:169], v[168:169], v[142:143]
	v_mul_f32_e32 v143, 0x3d372713, v144
	v_mul_f32_e32 v143, v144, v143
	v_fma_f32 v143, v144, v143, v144
	v_mul_f32_e32 v143, 0x3fcc422a, v143
	v_mul_f32_e32 v143, 0xbfb8aa3b, v143
	v_exp_f32_e32 v143, v143
	v_mul_f32_e32 v176, v167, v167
	v_add_f32_e32 v170, v167, v171
	v_cvt_pk_bf16_f32 v142, v166, v167
	v_add_f32_e32 v143, 1.0, v143
	v_rcp_f32_e32 v172, v143
	v_mul_f32_e32 v143, 0x3d372713, v145
	v_mul_f32_e32 v143, v145, v143
	v_fma_f32 v143, v145, v143, v145
	v_mul_f32_e32 v143, 0x3fcc422a, v143
	v_mul_f32_e32 v143, 0xbfb8aa3b, v143
	v_exp_f32_e32 v143, v143
	v_pk_add_f32 v[168:169], v[176:177], v[168:169] op_sel_hi:[0,1]
	v_add_f32_e32 v143, 1.0, v143
	v_rcp_f32_e32 v173, v143
	s_nop 0
	v_pk_mul_f32 v[174:175], v[144:145], v[172:173]
	s_nop 0
	v_mov_b32_e32 v166, v174
	v_mov_b32_e32 v171, v175
	v_pk_fma_f32 v[166:167], v[166:167], v[166:167], v[168:169]
	v_pk_fma_f32 v[144:145], v[144:145], v[172:173], v[170:171]
	v_pk_mul_f32 v[168:169], v[174:175], v[174:175]
	v_pk_mov_b32 v[166:167], v[174:175], v[166:167] op_sel:[1,0]
	v_mov_b32_e32 v145, v169
	v_pk_add_f32 v[144:145], v[144:145], v[166:167]
	v_cvt_pk_bf16_f32 v143, v174, v175
	global_store_dwordx4 v[138:139], v[140:143], off offset:256
	v_mov_b32_e32 v138, v144
	s_nop 1
	v_permlane16_swap_b32_e32 v138, v144
	v_mov_b32_e32 v139, v145
	s_nop 1
	v_permlane16_swap_b32_e32 v139, v145
	s_waitcnt lgkmcnt(0)
	v_pk_add_f32 v[138:139], v[144:145], v[138:139]
	s_nop 0
	v_mov_b32_e32 v140, v138
	s_nop 1
	v_permlane32_swap_b32_e32 v140, v138
	v_mov_b32_e32 v141, v139
	s_nop 1
	v_permlane32_swap_b32_e32 v141, v139
	s_and_saveexec_b64 s[10:11], vcc
	s_cbranch_execz .LBB0_882
	v_lshlrev_b64 v[136:137], 7, v[136:137]
	v_lshl_add_u64 v[136:137], s[0:1], 0, v[136:137]
	s_waitcnt lgkmcnt(0)
	v_pk_add_f32 v[138:139], v[138:139], v[140:141]
	global_store_dwordx2 v[136:137], v[138:139], off
.LBB0_882:
	s_or_b64 exec, exec, s[10:11]
	s_waitcnt lgkmcnt(0)
	v_pk_mul_f32 v[140:141], v[46:47], v[160:161] op_sel:[0,1]
	v_pk_mul_f32 v[144:145], v[48:49], v[160:161] op_sel:[0,1]
	v_mul_f32_e32 v142, 0x3d372713, v140
	v_mul_f32_e32 v143, 0x3d372713, v141
	v_mul_f32_e32 v142, v140, v142
	v_mul_f32_e32 v143, v141, v143
	v_fma_f32 v142, v140, v142, v140
	v_fma_f32 v143, v141, v143, v141
	v_mul_f32_e32 v166, 0x3d372713, v144
	v_mul_f32_e32 v167, 0x3d372713, v145
	v_mul_f32_e32 v142, 0x3fcc422a, v142
	v_mul_f32_e32 v143, 0x3fcc422a, v143
	v_mul_f32_e32 v166, v144, v166
	v_mul_f32_e32 v167, v145, v167
	v_mul_f32_e32 v142, 0xbfb8aa3b, v142
	v_mul_f32_e32 v143, 0xbfb8aa3b, v143
	v_fma_f32 v166, v144, v166, v144
	v_fma_f32 v167, v145, v167, v145
	v_exp_f32_e32 v142, v142
	v_exp_f32_e32 v143, v143
	v_mul_f32_e32 v166, 0x3fcc422a, v166
	v_mul_f32_e32 v167, 0x3fcc422a, v167
	v_mul_f32_e32 v166, 0xbfb8aa3b, v166
	v_mul_f32_e32 v167, 0xbfb8aa3b, v167
	v_exp_f32_e32 v166, v166
	v_exp_f32_e32 v167, v167
	v_add_f32_e32 v142, 1.0, v142
	v_add_f32_e32 v143, 1.0, v143
	v_rcp_f32_e32 v142, v142
	v_rcp_f32_e32 v143, v143
	v_add_f32_e32 v166, 1.0, v166
	v_add_f32_e32 v167, 1.0, v167
	v_rcp_f32_e32 v166, v166
	v_rcp_f32_e32 v167, v167
	v_pk_mul_f32 v[140:141], v[140:141], v[142:143]
	v_add_u32_e32 v136, 0x90, v158
	v_add_f32_e32 v142, 0, v140
	v_add_f32_e32 v168, v141, v142
	v_pk_mul_f32 v[144:145], v[144:145], v[166:167]
	v_mul_f32_e32 v142, v141, v141
	v_add_f32_e32 v166, v144, v168
	v_add_f32_e32 v170, v145, v166
	v_pk_mul_f32 v[166:167], v[42:43], v[160:161] op_sel:[0,1]
	v_pk_fma_f32 v[142:143], v[140:141], v[140:141], v[142:143] op_sel_hi:[1,1,0]
	v_mul_f32_e32 v168, 0x3d372713, v166
	v_mul_f32_e32 v169, 0x3d372713, v167
	v_mul_f32_e32 v168, v166, v168
	v_mul_f32_e32 v169, v167, v169
	v_fma_f32 v168, v166, v168, v166
	v_fma_f32 v169, v167, v169, v167
	v_mul_f32_e32 v168, 0x3fcc422a, v168
	v_mul_f32_e32 v169, 0x3fcc422a, v169
	v_mul_f32_e32 v168, 0xbfb8aa3b, v168
	v_mul_f32_e32 v169, 0xbfb8aa3b, v169
	v_exp_f32_e32 v168, v168
	v_exp_f32_e32 v169, v169
	v_pk_fma_f32 v[142:143], v[144:145], v[144:145], v[142:143]
	v_ashrrev_i32_e32 v137, 31, v136
	v_add_f32_e32 v168, 1.0, v168
	v_add_f32_e32 v169, 1.0, v169
	v_rcp_f32_e32 v168, v168
	v_rcp_f32_e32 v169, v169
	v_lshlrev_b64 v[138:139], 11, v[136:137]
	v_lshl_add_u64 v[138:139], v[134:135], 0, v[138:139]
	v_cvt_pk_bf16_f32 v140, v140, v141
	v_pk_mul_f32 v[166:167], v[166:167], v[168:169]
	v_mov_b32_e32 v169, v145
	v_add_f32_e32 v171, v166, v170
	v_mul_f32_e32 v170, v145, v145
	v_mov_b32_e32 v168, v166
	v_pk_add_f32 v[142:143], v[170:171], v[142:143] op_sel_hi:[0,1]
	v_pk_fma_f32 v[142:143], v[168:169], v[168:169], v[142:143]
; __device__ __forceinline__ u32x4 pack8(const float* v) { u32x4 w; w.x = cvtpk(v[0], v[1]); w.y = cvtpk(v[2], v[3]); w.z = cvtpk(v[4], v[5]); w.w = cvtpk(v[6], v[7]); return w; }
; __device__ __forceinline__ float sigm(float x) { return __builtin_amdgcn_rcpf(1.f + __expf(-x)); }
; __device__ __forceinline__ float siluf_(float x) { return x * sigm(x); }
; __device__ __forceinline__ float gelu_tanh(float x) { return x * sigm(1.5957691216f * (x + 0.044715f * x * x * x)); }
;     template <int KIND>
;     __device__ __forceinline__ void act_tile(const pg8::f32x4 (&acc)[2][2][4][2], const float (&rs)[2][4], unsigned char* w_, int row0, int colt, int statslot, int fq_) const {
;     ...
;                 for (int bj = 0; bj < 2; ++bj) {
;                     float v[8];
; #pragma unroll
;                     for (int n = 0; n < 2; ++n)
; #pragma unroll
;                         for (int j = 0; j < 4; ++j) {
;                             const float a = acc[ai][bj][m][n][j] * rs[ai][m];
;                             const float r = KIND == 2 ? sigm(a) : gelu_tanh(a);
;                             v[n * 4 + j] = r;
;                             if (KIND == 1) { s1 += r; s2 += r * r; }
;                         }
;                     *(u32x4*)(base + (size_t)row * ldc + colt + bj * 128) = pack8(v);
;                 }
;                 if (KIND == 1) {
;                     s1 += __shfl_xor(s1, 16); s1 += __shfl_xor(s1, 32); s2 += __shfl_xor(s2, 16); s2 += __shfl_xor(s2, 32);
;                     if (fq_ == 0) { float* sp = (float*)(w_ + WS_VSTAT) + ((size_t)row * 16 + statslot) * 2; sp[0] = s1; sp[1] = s2; }
;                 }
	v_pk_mul_f32 v[168:169], v[44:45], v[160:161] op_sel:[0,1]
	v_add_f32_e32 v172, v167, v171
	v_mul_f32_e32 v170, 0x3d372713, v168
	v_mul_f32_e32 v171, 0x3d372713, v169
	v_mul_f32_e32 v170, v168, v170
	v_mul_f32_e32 v171, v169, v171
	v_fma_f32 v170, v168, v170, v168
	v_fma_f32 v171, v169, v171, v169
	v_mul_f32_e32 v170, 0x3fcc422a, v170
	v_mul_f32_e32 v171, 0x3fcc422a, v171
	v_mul_f32_e32 v170, 0xbfb8aa3b, v170
	v_mul_f32_e32 v171, 0xbfb8aa3b, v171
	v_exp_f32_e32 v170, v170
	v_exp_f32_e32 v171, v171
	v_cvt_pk_bf16_f32 v141, v144, v145
	v_add_f32_e32 v170, 1.0, v170
	v_add_f32_e32 v171, 1.0, v171
	v_rcp_f32_e32 v170, v170
	v_rcp_f32_e32 v171, v171
	s_nop 0
	v_pk_mul_f32 v[168:169], v[168:169], v[170:171]
	s_nop 0
	v_add_f32_e32 v173, v168, v172
	v_mul_f32_e32 v172, v167, v167
	v_mov_b32_e32 v170, v168
	v_mov_b32_e32 v171, v167
	v_pk_add_f32 v[142:143], v[172:173], v[142:143] op_sel_hi:[0,1]
	v_pk_fma_f32 v[170:171], v[170:171], v[170:171], v[142:143]
	v_cvt_pk_bf16_f32 v142, v166, v167
	v_cvt_pk_bf16_f32 v143, v168, v169
	global_store_dwordx4 v[138:139], v[140:143], off
	v_add_f32_e32 v172, v169, v173
	s_nop 0
	v_pk_mul_f32 v[140:141], v[38:39], v[160:161] op_sel:[0,1]
	s_nop 0
	v_mul_f32_e32 v142, 0x3d372713, v140
	v_mul_f32_e32 v143, 0x3d372713, v141
	v_mul_f32_e32 v142, v140, v142
	v_mul_f32_e32 v143, v141, v143
	v_fma_f32 v142, v140, v142, v140
	v_fma_f32 v143, v141, v143, v141
	v_mul_f32_e32 v142, 0x3fcc422a, v142
	v_mul_f32_e32 v143, 0x3fcc422a, v143
	v_mul_f32_e32 v142, 0xbfb8aa3b, v142
	v_mul_f32_e32 v143, 0xbfb8aa3b, v143
	v_exp_f32_e32 v142, v142
	v_exp_f32_e32 v143, v143
	v_add_f32_e32 v142, 1.0, v142
	v_add_f32_e32 v143, 1.0, v143
	v_rcp_f32_e32 v142, v142
	v_rcp_f32_e32 v143, v143
	s_nop 0
	v_pk_mul_f32 v[140:141], v[140:141], v[142:143]
	v_mul_f32_e32 v142, v169, v169
	v_add_f32_e32 v144, v140, v172
	v_mov_b32_e32 v168, v140
	v_pk_add_f32 v[142:143], v[142:143], v[170:171] op_sel_hi:[0,1]
	v_pk_fma_f32 v[142:143], v[168:169], v[168:169], v[142:143]
	v_add_f32_e32 v168, v141, v144
	v_pk_mul_f32 v[144:145], v[40:41], v[160:161] op_sel:[0,1]
	v_cvt_pk_bf16_f32 v140, v140, v141
	v_mul_f32_e32 v166, 0x3d372713, v144
	v_mul_f32_e32 v167, 0x3d372713, v145
	v_mul_f32_e32 v166, v144, v166
	v_mul_f32_e32 v167, v145, v167
	v_fma_f32 v166, v144, v166, v144
	v_fma_f32 v167, v145, v167, v145
	v_mul_f32_e32 v166, 0x3fcc422a, v166
	v_mul_f32_e32 v167, 0x3fcc422a, v167
	v_mul_f32_e32 v166, 0xbfb8aa3b, v166
	v_mul_f32_e32 v167, 0xbfb8aa3b, v167
	v_exp_f32_e32 v166, v166
	v_exp_f32_e32 v167, v167
	v_add_f32_e32 v166, 1.0, v166
	v_add_f32_e32 v167, 1.0, v167
	v_rcp_f32_e32 v166, v166
	v_rcp_f32_e32 v167, v167
	s_nop 0
	v_pk_mul_f32 v[144:145], v[144:145], v[166:167]
	s_nop 0
	v_add_f32_e32 v169, v144, v168
	v_mul_f32_e32 v168, v141, v141
	v_mov_b32_e32 v166, v144
	v_mov_b32_e32 v167, v141
	v_pk_add_f32 v[142:143], v[168:169], v[142:143] op_sel_hi:[0,1]
	v_pk_fma_f32 v[142:143], v[166:167], v[166:167], v[142:143]
	v_pk_mul_f32 v[166:167], v[34:35], v[160:161] op_sel:[0,1]
	v_add_f32_e32 v170, v145, v169
	v_mul_f32_e32 v168, 0x3d372713, v166
	v_mul_f32_e32 v169, 0x3d372713, v167
	v_mul_f32_e32 v168, v166, v168
	v_mul_f32_e32 v169, v167, v169
	v_fma_f32 v168, v166, v168, v166
	v_fma_f32 v169, v167, v169, v167
	v_mul_f32_e32 v168, 0x3fcc422a, v168
	v_mul_f32_e32 v169, 0x3fcc422a, v169
	v_mul_f32_e32 v168, 0xbfb8aa3b, v168
	v_mul_f32_e32 v169, 0xbfb8aa3b, v169
	v_exp_f32_e32 v168, v168
	v_exp_f32_e32 v169, v169
	v_cvt_pk_bf16_f32 v141, v144, v145
	v_add_f32_e32 v168, 1.0, v168
	v_add_f32_e32 v169, 1.0, v169
	v_rcp_f32_e32 v168, v168
	v_rcp_f32_e32 v169, v169
	s_nop 0
	v_pk_mul_f32 v[166:167], v[166:167], v[168:169]
	s_nop 0
	v_add_f32_e32 v171, v166, v170
	v_mul_f32_e32 v170, v145, v145
	v_mov_b32_e32 v168, v166
	v_mov_b32_e32 v169, v145
	v_pk_add_f32 v[142:143], v[170:171], v[142:143] op_sel_hi:[0,1]
	v_pk_mul_f32 v[144:145], v[36:37], v[160:161] op_sel:[0,1]
	v_pk_fma_f32 v[168:169], v[168:169], v[168:169], v[142:143]
	v_mul_f32_e32 v143, 0x3d372713, v144
	v_mul_f32_e32 v143, v144, v143
	v_fma_f32 v143, v144, v143, v144
	v_mul_f32_e32 v143, 0x3fcc422a, v143
	v_mul_f32_e32 v143, 0xbfb8aa3b, v143
	v_exp_f32_e32 v143, v143
	v_mul_f32_e32 v176, v167, v167
	v_add_f32_e32 v170, v167, v171
	v_cvt_pk_bf16_f32 v142, v166, v167
	v_add_f32_e32 v143, 1.0, v143
	v_rcp_f32_e32 v172, v143
	v_mul_f32_e32 v143, 0x3d372713, v145
	v_mul_f32_e32 v143, v145, v143
	v_fma_f32 v143, v145, v143, v145
	v_mul_f32_e32 v143, 0x3fcc422a, v143
	v_mul_f32_e32 v143, 0xbfb8aa3b, v143
	v_exp_f32_e32 v143, v143
	v_pk_add_f32 v[168:169], v[176:177], v[168:169] op_sel_hi:[0,1]
	v_add_f32_e32 v143, 1.0, v143
	v_rcp_f32_e32 v173, v143
	s_nop 0
	v_pk_mul_f32 v[174:175], v[144:145], v[172:173]
	s_nop 0
	v_mov_b32_e32 v166, v174
	v_mov_b32_e32 v171, v175
	v_pk_fma_f32 v[166:167], v[166:167], v[166:167], v[168:169]
	v_pk_fma_f32 v[144:145], v[144:145], v[172:173], v[170:171]
	v_pk_mul_f32 v[168:169], v[174:175], v[174:175]
	v_pk_mov_b32 v[166:167], v[174:175], v[166:167] op_sel:[1,0]
	v_mov_b32_e32 v145, v169
	v_pk_add_f32 v[144:145], v[144:145], v[166:167]
	v_cvt_pk_bf16_f32 v143, v174, v175
	global_store_dwordx4 v[138:139], v[140:143], off offset:256
	v_mov_b32_e32 v138, v144
	s_nop 1
	v_permlane16_swap_b32_e32 v138, v144
	v_mov_b32_e32 v139, v145
	s_nop 1
	v_permlane16_swap_b32_e32 v139, v145
	s_waitcnt lgkmcnt(0)
	v_pk_add_f32 v[138:139], v[144:145], v[138:139]
	s_nop 0
	v_mov_b32_e32 v140, v138
	s_nop 1
	v_permlane32_swap_b32_e32 v140, v138
	v_mov_b32_e32 v141, v139
	s_nop 1
	v_permlane32_swap_b32_e32 v141, v139
	s_and_saveexec_b64 s[10:11], vcc
	s_cbranch_execz .LBB0_884
	v_lshlrev_b64 v[136:137], 7, v[136:137]
	v_lshl_add_u64 v[136:137], s[0:1], 0, v[136:137]
	s_waitcnt lgkmcnt(0)
	v_pk_add_f32 v[138:139], v[138:139], v[140:141]
	global_store_dwordx2 v[136:137], v[138:139], off
; __device__ __forceinline__ u32x4 pack8(const float* v) { u32x4 w; w.x = cvtpk(v[0], v[1]); w.y = cvtpk(v[2], v[3]); w.z = cvtpk(v[4], v[5]); w.w = cvtpk(v[6], v[7]); return w; }
; __device__ __forceinline__ float sigm(float x) { return __builtin_amdgcn_rcpf(1.f + __expf(-x)); }
; __device__ __forceinline__ float siluf_(float x) { return x * sigm(x); }
; __device__ __forceinline__ float gelu_tanh(float x) { return x * sigm(1.5957691216f * (x + 0.044715f * x * x * x)); }
;     template <int KIND>
;     __device__ __forceinline__ void act_tile(const pg8::f32x4 (&acc)[2][2][4][2], const float (&rs)[2][4], unsigned char* w_, int row0, int colt, int statslot, int fq_) const {
;     ...
; #pragma unroll
;         for (int ai = 0; ai < 2; ++ai)
; #pragma unroll
;             for (int m = 0; m < 4; ++m) {
;                 const int row = row0 + ai * 128 + m * 16;
;                 float s1 = 0.f, s2 = 0.f;
; #pragma unroll
;                 for (int bj = 0; bj < 2; ++bj) {
;                     float v[8];
; #pragma unroll
;                     for (int n = 0; n < 2; ++n)
; #pragma unroll
;                         for (int j = 0; j < 4; ++j) {
;                             const float a = acc[ai][bj][m][n][j] * rs[ai][m];
;                             const float r = KIND == 2 ? sigm(a) : gelu_tanh(a);
;                             v[n * 4 + j] = r;
;                             if (KIND == 1) { s1 += r; s2 += r * r; }
;                         }
;                     *(u32x4*)(base + (size_t)row * ldc + colt + bj * 128) = pack8(v);
.LBB0_884:
	s_or_b64 exec, exec, s[10:11]
	s_waitcnt lgkmcnt(0)
	v_pk_mul_f32 v[140:141], v[30:31], v[132:133] op_sel_hi:[1,0]
	v_pk_mul_f32 v[144:145], v[32:33], v[132:133] op_sel_hi:[1,0]
	v_mul_f32_e32 v142, 0x3d372713, v140
	v_mul_f32_e32 v143, 0x3d372713, v141
	v_mul_f32_e32 v142, v140, v142
	v_mul_f32_e32 v143, v141, v143
	v_fma_f32 v142, v140, v142, v140
	v_fma_f32 v143, v141, v143, v141
	v_mul_f32_e32 v166, 0x3d372713, v144
	v_mul_f32_e32 v167, 0x3d372713, v145
	v_mul_f32_e32 v142, 0x3fcc422a, v142
	v_mul_f32_e32 v143, 0x3fcc422a, v143
	v_mul_f32_e32 v166, v144, v166
	v_mul_f32_e32 v167, v145, v167
	v_mul_f32_e32 v142, 0xbfb8aa3b, v142
	v_mul_f32_e32 v143, 0xbfb8aa3b, v143
	v_fma_f32 v166, v144, v166, v144
	v_fma_f32 v167, v145, v167, v145
	v_exp_f32_e32 v142, v142
	v_exp_f32_e32 v143, v143
	v_mul_f32_e32 v166, 0x3fcc422a, v166
	v_mul_f32_e32 v167, 0x3fcc422a, v167
	v_mul_f32_e32 v166, 0xbfb8aa3b, v166
	v_mul_f32_e32 v167, 0xbfb8aa3b, v167
	v_exp_f32_e32 v166, v166
	v_exp_f32_e32 v167, v167
	v_add_f32_e32 v142, 1.0, v142
	v_add_f32_e32 v143, 1.0, v143
	v_rcp_f32_e32 v142, v142
	v_rcp_f32_e32 v143, v143
	v_add_f32_e32 v166, 1.0, v166
	v_add_f32_e32 v167, 1.0, v167
	v_rcp_f32_e32 v166, v166
	v_rcp_f32_e32 v167, v167
	v_pk_mul_f32 v[140:141], v[140:141], v[142:143]
	v_add_u32_e32 v136, 0xa0, v158
	v_add_f32_e32 v142, 0, v140
	v_add_f32_e32 v168, v141, v142
	v_pk_mul_f32 v[144:145], v[144:145], v[166:167]
	v_mul_f32_e32 v142, v141, v141
	v_add_f32_e32 v166, v144, v168
	v_add_f32_e32 v170, v145, v166
	v_pk_mul_f32 v[166:167], v[26:27], v[132:133] op_sel_hi:[1,0]
	v_pk_fma_f32 v[142:143], v[140:141], v[140:141], v[142:143] op_sel_hi:[1,1,0]
	v_mul_f32_e32 v168, 0x3d372713, v166
	v_mul_f32_e32 v169, 0x3d372713, v167
	v_mul_f32_e32 v168, v166, v168
	v_mul_f32_e32 v169, v167, v169
	v_fma_f32 v168, v166, v168, v166
	v_fma_f32 v169, v167, v169, v167
	v_mul_f32_e32 v168, 0x3fcc422a, v168
	v_mul_f32_e32 v169, 0x3fcc422a, v169
	v_mul_f32_e32 v168, 0xbfb8aa3b, v168
	v_mul_f32_e32 v169, 0xbfb8aa3b, v169
	v_exp_f32_e32 v168, v168
	v_exp_f32_e32 v169, v169
	v_pk_fma_f32 v[142:143], v[144:145], v[144:145], v[142:143]
	v_ashrrev_i32_e32 v137, 31, v136
	v_add_f32_e32 v168, 1.0, v168
	v_add_f32_e32 v169, 1.0, v169
	v_rcp_f32_e32 v168, v168
	v_rcp_f32_e32 v169, v169
	v_lshlrev_b64 v[138:139], 11, v[136:137]
	v_lshl_add_u64 v[138:139], v[134:135], 0, v[138:139]
	v_cvt_pk_bf16_f32 v140, v140, v141
	v_pk_mul_f32 v[166:167], v[166:167], v[168:169]
	v_mov_b32_e32 v169, v145
	v_add_f32_e32 v171, v166, v170
	v_mul_f32_e32 v170, v145, v145
	v_mov_b32_e32 v168, v166
	v_pk_add_f32 v[142:143], v[170:171], v[142:143] op_sel_hi:[0,1]
	v_pk_fma_f32 v[142:143], v[168:169], v[168:169], v[142:143]
	v_pk_mul_f32 v[168:169], v[28:29], v[132:133] op_sel_hi:[1,0]
	v_add_f32_e32 v172, v167, v171
	v_mul_f32_e32 v170, 0x3d372713, v168
	v_mul_f32_e32 v171, 0x3d372713, v169
	v_mul_f32_e32 v170, v168, v170
	v_mul_f32_e32 v171, v169, v171
	v_fma_f32 v170, v168, v170, v168
	v_fma_f32 v171, v169, v171, v169
	v_mul_f32_e32 v170, 0x3fcc422a, v170
	v_mul_f32_e32 v171, 0x3fcc422a, v171
	v_mul_f32_e32 v170, 0xbfb8aa3b, v170
	v_mul_f32_e32 v171, 0xbfb8aa3b, v171
	v_exp_f32_e32 v170, v170
	v_exp_f32_e32 v171, v171
	v_cvt_pk_bf16_f32 v141, v144, v145
	v_add_f32_e32 v170, 1.0, v170
	v_add_f32_e32 v171, 1.0, v171
	v_rcp_f32_e32 v170, v170
	v_rcp_f32_e32 v171, v171
	s_nop 0
	v_pk_mul_f32 v[168:169], v[168:169], v[170:171]
	s_nop 0
	v_add_f32_e32 v173, v168, v172
	v_mul_f32_e32 v172, v167, v167
	v_mov_b32_e32 v170, v168
	v_mov_b32_e32 v171, v167
	v_pk_add_f32 v[142:143], v[172:173], v[142:143] op_sel_hi:[0,1]
	v_pk_fma_f32 v[170:171], v[170:171], v[170:171], v[142:143]
	v_cvt_pk_bf16_f32 v142, v166, v167
	v_cvt_pk_bf16_f32 v143, v168, v169
	global_store_dwordx4 v[138:139], v[140:143], off
	v_add_f32_e32 v172, v169, v173
	s_nop 0
	v_pk_mul_f32 v[140:141], v[22:23], v[132:133] op_sel_hi:[1,0]
	s_nop 0
	v_mul_f32_e32 v142, 0x3d372713, v140
	v_mul_f32_e32 v143, 0x3d372713, v141
	v_mul_f32_e32 v142, v140, v142
	v_mul_f32_e32 v143, v141, v143
	v_fma_f32 v142, v140, v142, v140
	v_fma_f32 v143, v141, v143, v141
	v_mul_f32_e32 v142, 0x3fcc422a, v142
	v_mul_f32_e32 v143, 0x3fcc422a, v143
	v_mul_f32_e32 v142, 0xbfb8aa3b, v142
	v_mul_f32_e32 v143, 0xbfb8aa3b, v143
	v_exp_f32_e32 v142, v142
	v_exp_f32_e32 v143, v143
	v_add_f32_e32 v142, 1.0, v142
	v_add_f32_e32 v143, 1.0, v143
	v_rcp_f32_e32 v142, v142
	v_rcp_f32_e32 v143, v143
	s_nop 0
	v_pk_mul_f32 v[140:141], v[140:141], v[142:143]
	v_mul_f32_e32 v142, v169, v169
	v_add_f32_e32 v144, v140, v172
	v_mov_b32_e32 v168, v140
	v_pk_add_f32 v[142:143], v[142:143], v[170:171] op_sel_hi:[0,1]
	v_pk_fma_f32 v[142:143], v[168:169], v[168:169], v[142:143]
	v_add_f32_e32 v168, v141, v144
	v_pk_mul_f32 v[144:145], v[24:25], v[132:133] op_sel_hi:[1,0]
	v_cvt_pk_bf16_f32 v140, v140, v141
	v_mul_f32_e32 v166, 0x3d372713, v144
	v_mul_f32_e32 v167, 0x3d372713, v145
	v_mul_f32_e32 v166, v144, v166
	v_mul_f32_e32 v167, v145, v167
	v_fma_f32 v166, v144, v166, v144
	v_fma_f32 v167, v145, v167, v145
	v_mul_f32_e32 v166, 0x3fcc422a, v166
	v_mul_f32_e32 v167, 0x3fcc422a, v167
	v_mul_f32_e32 v166, 0xbfb8aa3b, v166
	v_mul_f32_e32 v167, 0xbfb8aa3b, v167
	v_exp_f32_e32 v166, v166
	v_exp_f32_e32 v167, v167
	v_add_f32_e32 v166, 1.0, v166
	v_add_f32_e32 v167, 1.0, v167
	v_rcp_f32_e32 v166, v166
	v_rcp_f32_e32 v167, v167
	s_nop 0
	v_pk_mul_f32 v[144:145], v[144:145], v[166:167]
	s_nop 0
	v_add_f32_e32 v169, v144, v168
	v_mul_f32_e32 v168, v141, v141
	v_mov_b32_e32 v166, v144
	v_mov_b32_e32 v167, v141
	v_pk_add_f32 v[142:143], v[168:169], v[142:143] op_sel_hi:[0,1]
; __device__ __forceinline__ u32x4 pack8(const float* v) { u32x4 w; w.x = cvtpk(v[0], v[1]); w.y = cvtpk(v[2], v[3]); w.z = cvtpk(v[4], v[5]); w.w = cvtpk(v[6], v[7]); return w; }
; __device__ __forceinline__ float sigm(float x) { return __builtin_amdgcn_rcpf(1.f + __expf(-x)); }
; __device__ __forceinline__ float siluf_(float x) { return x * sigm(x); }
; __device__ __forceinline__ float gelu_tanh(float x) { return x * sigm(1.5957691216f * (x + 0.044715f * x * x * x)); }
;     template <int KIND>
;     __device__ __forceinline__ void act_tile(const pg8::f32x4 (&acc)[2][2][4][2], const float (&rs)[2][4], unsigned char* w_, int row0, int colt, int statslot, int fq_) const {
;     ...
;                 for (int bj = 0; bj < 2; ++bj) {
;                     float v[8];
; #pragma unroll
;                     for (int n = 0; n < 2; ++n)
; #pragma unroll
;                         for (int j = 0; j < 4; ++j) {
;                             const float a = acc[ai][bj][m][n][j] * rs[ai][m];
;                             const float r = KIND == 2 ? sigm(a) : gelu_tanh(a);
;                             v[n * 4 + j] = r;
;                             if (KIND == 1) { s1 += r; s2 += r * r; }
;                         }
;                     *(u32x4*)(base + (size_t)row * ldc + colt + bj * 128) = pack8(v);
;                 }
;                 if (KIND == 1) {
;                     s1 += __shfl_xor(s1, 16); s1 += __shfl_xor(s1, 32); s2 += __shfl_xor(s2, 16); s2 += __shfl_xor(s2, 32);
;                     if (fq_ == 0) { float* sp = (float*)(w_ + WS_VSTAT) + ((size_t)row * 16 + statslot) * 2; sp[0] = s1; sp[1] = s2; }
;                 }
	v_pk_fma_f32 v[142:143], v[166:167], v[166:167], v[142:143]
	v_pk_mul_f32 v[166:167], v[18:19], v[132:133] op_sel_hi:[1,0]
	v_add_f32_e32 v170, v145, v169
	v_mul_f32_e32 v168, 0x3d372713, v166
	v_mul_f32_e32 v169, 0x3d372713, v167
	v_mul_f32_e32 v168, v166, v168
	v_mul_f32_e32 v169, v167, v169
	v_fma_f32 v168, v166, v168, v166
	v_fma_f32 v169, v167, v169, v167
	v_mul_f32_e32 v168, 0x3fcc422a, v168
	v_mul_f32_e32 v169, 0x3fcc422a, v169
	v_mul_f32_e32 v168, 0xbfb8aa3b, v168
	v_mul_f32_e32 v169, 0xbfb8aa3b, v169
	v_exp_f32_e32 v168, v168
	v_exp_f32_e32 v169, v169
	v_cvt_pk_bf16_f32 v141, v144, v145
	v_add_f32_e32 v168, 1.0, v168
	v_add_f32_e32 v169, 1.0, v169
	v_rcp_f32_e32 v168, v168
	v_rcp_f32_e32 v169, v169
	s_nop 0
	v_pk_mul_f32 v[166:167], v[166:167], v[168:169]
	s_nop 0
	v_add_f32_e32 v171, v166, v170
	v_mul_f32_e32 v170, v145, v145
	v_mov_b32_e32 v168, v166
	v_mov_b32_e32 v169, v145
	v_pk_add_f32 v[142:143], v[170:171], v[142:143] op_sel_hi:[0,1]
	v_pk_mul_f32 v[144:145], v[20:21], v[132:133] op_sel_hi:[1,0]
	v_pk_fma_f32 v[168:169], v[168:169], v[168:169], v[142:143]
	v_mul_f32_e32 v143, 0x3d372713, v144
	v_mul_f32_e32 v143, v144, v143
	v_fma_f32 v143, v144, v143, v144
	v_mul_f32_e32 v143, 0x3fcc422a, v143
	v_mul_f32_e32 v143, 0xbfb8aa3b, v143
	v_exp_f32_e32 v143, v143
	v_mul_f32_e32 v176, v167, v167
	v_add_f32_e32 v170, v167, v171
	v_cvt_pk_bf16_f32 v142, v166, v167
	v_add_f32_e32 v143, 1.0, v143
	v_rcp_f32_e32 v172, v143
	v_mul_f32_e32 v143, 0x3d372713, v145
	v_mul_f32_e32 v143, v145, v143
	v_fma_f32 v143, v145, v143, v145
	v_mul_f32_e32 v143, 0x3fcc422a, v143
	v_mul_f32_e32 v143, 0xbfb8aa3b, v143
	v_exp_f32_e32 v143, v143
	v_pk_add_f32 v[168:169], v[176:177], v[168:169] op_sel_hi:[0,1]
	v_add_f32_e32 v143, 1.0, v143
	v_rcp_f32_e32 v173, v143
	s_nop 0
	v_pk_mul_f32 v[174:175], v[144:145], v[172:173]
	s_nop 0
	v_mov_b32_e32 v166, v174
	v_mov_b32_e32 v171, v175
	v_pk_fma_f32 v[166:167], v[166:167], v[166:167], v[168:169]
	v_pk_fma_f32 v[144:145], v[144:145], v[172:173], v[170:171]
	v_pk_mul_f32 v[168:169], v[174:175], v[174:175]
	v_pk_mov_b32 v[166:167], v[174:175], v[166:167] op_sel:[1,0]
	v_mov_b32_e32 v145, v169
	v_pk_add_f32 v[144:145], v[144:145], v[166:167]
	v_cvt_pk_bf16_f32 v143, v174, v175
	global_store_dwordx4 v[138:139], v[140:143], off offset:256
	v_mov_b32_e32 v138, v144
	s_nop 1
	v_permlane16_swap_b32_e32 v138, v144
	v_mov_b32_e32 v139, v145
	s_nop 1
	v_permlane16_swap_b32_e32 v139, v145
	s_waitcnt lgkmcnt(0)
	v_pk_add_f32 v[138:139], v[144:145], v[138:139]
	s_nop 0
	v_mov_b32_e32 v140, v138
	s_nop 1
	v_permlane32_swap_b32_e32 v140, v138
	v_mov_b32_e32 v141, v139
	s_nop 1
	v_permlane32_swap_b32_e32 v141, v139
	s_and_saveexec_b64 s[10:11], vcc
	s_cbranch_execz .LBB0_886
	v_lshlrev_b64 v[136:137], 7, v[136:137]
	v_lshl_add_u64 v[136:137], s[0:1], 0, v[136:137]
	s_waitcnt lgkmcnt(0)
	v_pk_add_f32 v[138:139], v[138:139], v[140:141]
	global_store_dwordx2 v[136:137], v[138:139], off
.LBB0_886:
	s_or_b64 exec, exec, s[10:11]
	v_add_u32_e32 v136, 0xb0, v158
	v_ashrrev_i32_e32 v137, 31, v136
	v_lshlrev_b64 v[138:139], 11, v[136:137]
	v_lshl_add_u64 v[134:135], v[134:135], 0, v[138:139]
	v_pk_mul_f32 v[138:139], v[14:15], v[132:133] op_sel:[0,1]
	v_pk_mul_f32 v[142:143], v[16:17], v[132:133] op_sel:[0,1]
	s_waitcnt lgkmcnt(0)
	v_mul_f32_e32 v140, 0x3d372713, v138
	v_mul_f32_e32 v141, 0x3d372713, v139
	v_mul_f32_e32 v140, v138, v140
	v_mul_f32_e32 v141, v139, v141
	v_fma_f32 v140, v138, v140, v138
	v_fma_f32 v141, v139, v141, v139
	v_mul_f32_e32 v144, 0x3d372713, v142
	v_mul_f32_e32 v145, 0x3d372713, v143
	v_mul_f32_e32 v140, 0x3fcc422a, v140
	v_mul_f32_e32 v141, 0x3fcc422a, v141
	v_mul_f32_e32 v144, v142, v144
	v_mul_f32_e32 v145, v143, v145
	v_mul_f32_e32 v140, 0xbfb8aa3b, v140
	v_mul_f32_e32 v141, 0xbfb8aa3b, v141
	v_fma_f32 v144, v142, v144, v142
	v_fma_f32 v145, v143, v145, v143
	v_exp_f32_e32 v140, v140
	v_exp_f32_e32 v141, v141
	v_mul_f32_e32 v144, 0x3fcc422a, v144
	v_mul_f32_e32 v145, 0x3fcc422a, v145
	v_mul_f32_e32 v144, 0xbfb8aa3b, v144
	v_mul_f32_e32 v145, 0xbfb8aa3b, v145
	v_exp_f32_e32 v144, v144
	v_exp_f32_e32 v145, v145
	v_add_f32_e32 v140, 1.0, v140
	v_add_f32_e32 v141, 1.0, v141
	v_rcp_f32_e32 v140, v140
	v_rcp_f32_e32 v141, v141
	v_add_f32_e32 v144, 1.0, v144
	v_add_f32_e32 v145, 1.0, v145
	v_rcp_f32_e32 v144, v144
	v_rcp_f32_e32 v145, v145
	v_pk_mul_f32 v[138:139], v[138:139], v[140:141]
	v_pk_mul_f32 v[142:143], v[142:143], v[144:145]
	v_add_f32_e32 v140, 0, v138
	v_add_f32_e32 v166, v139, v140
	v_add_f32_e32 v144, v142, v166
	v_add_f32_e32 v168, v143, v144
	v_pk_mul_f32 v[144:145], v[10:11], v[132:133] op_sel:[0,1]
	v_mul_f32_e32 v140, v139, v139
	v_mul_f32_e32 v166, 0x3d372713, v144
	v_mul_f32_e32 v167, 0x3d372713, v145
	v_mul_f32_e32 v166, v144, v166
	v_mul_f32_e32 v167, v145, v167
	v_fma_f32 v166, v144, v166, v144
	v_fma_f32 v167, v145, v167, v145
	v_mul_f32_e32 v166, 0x3fcc422a, v166
	v_mul_f32_e32 v167, 0x3fcc422a, v167
	v_mul_f32_e32 v166, 0xbfb8aa3b, v166
	v_mul_f32_e32 v167, 0xbfb8aa3b, v167
	v_exp_f32_e32 v166, v166
	v_exp_f32_e32 v167, v167
	v_pk_fma_f32 v[140:141], v[138:139], v[138:139], v[140:141] op_sel_hi:[1,1,0]
	v_cvt_pk_bf16_f32 v138, v138, v139
	v_add_f32_e32 v166, 1.0, v166
	v_add_f32_e32 v167, 1.0, v167
	v_rcp_f32_e32 v166, v166
	v_rcp_f32_e32 v167, v167
	v_pk_fma_f32 v[140:141], v[142:143], v[142:143], v[140:141]
	v_cvt_pk_bf16_f32 v139, v142, v143
	v_pk_mul_f32 v[144:145], v[144:145], v[166:167]
	s_nop 0
	v_add_f32_e32 v169, v144, v168
	v_mul_f32_e32 v168, v143, v143
	v_mov_b32_e32 v166, v144
	v_mov_b32_e32 v167, v143
	v_pk_add_f32 v[140:141], v[168:169], v[140:141] op_sel_hi:[0,1]
; __device__ __forceinline__ u32x4 pack8(const float* v) { u32x4 w; w.x = cvtpk(v[0], v[1]); w.y = cvtpk(v[2], v[3]); w.z = cvtpk(v[4], v[5]); w.w = cvtpk(v[6], v[7]); return w; }
; __device__ __forceinline__ float sigm(float x) { return __builtin_amdgcn_rcpf(1.f + __expf(-x)); }
; __device__ __forceinline__ float siluf_(float x) { return x * sigm(x); }
; __device__ __forceinline__ float gelu_tanh(float x) { return x * sigm(1.5957691216f * (x + 0.044715f * x * x * x)); }
;     template <int KIND>
;     __device__ __forceinline__ void act_tile(const pg8::f32x4 (&acc)[2][2][4][2], const float (&rs)[2][4], unsigned char* w_, int row0, int colt, int statslot, int fq_) const {
;     ...
;                 for (int bj = 0; bj < 2; ++bj) {
;                     float v[8];
; #pragma unroll
;                     for (int n = 0; n < 2; ++n)
; #pragma unroll
;                         for (int j = 0; j < 4; ++j) {
;                             const float a = acc[ai][bj][m][n][j] * rs[ai][m];
;                             const float r = KIND == 2 ? sigm(a) : gelu_tanh(a);
;                             v[n * 4 + j] = r;
;                             if (KIND == 1) { s1 += r; s2 += r * r; }
;                         }
;                     *(u32x4*)(base + (size_t)row * ldc + colt + bj * 128) = pack8(v);
;                 }
;                 if (KIND == 1) {
;                     s1 += __shfl_xor(s1, 16); s1 += __shfl_xor(s1, 32); s2 += __shfl_xor(s2, 16); s2 += __shfl_xor(s2, 32);
;                     if (fq_ == 0) { float* sp = (float*)(w_ + WS_VSTAT) + ((size_t)row * 16 + statslot) * 2; sp[0] = s1; sp[1] = s2; }
;                 }
	v_pk_fma_f32 v[140:141], v[166:167], v[166:167], v[140:141]
	v_pk_mul_f32 v[166:167], v[12:13], v[132:133] op_sel:[0,1]
	v_add_f32_e32 v170, v145, v169
	v_mul_f32_e32 v168, 0x3d372713, v166
	v_mul_f32_e32 v169, 0x3d372713, v167
	v_mul_f32_e32 v168, v166, v168
	v_mul_f32_e32 v169, v167, v169
	v_fma_f32 v168, v166, v168, v166
	v_fma_f32 v169, v167, v169, v167
	v_mul_f32_e32 v168, 0x3fcc422a, v168
	v_mul_f32_e32 v169, 0x3fcc422a, v169
	v_mul_f32_e32 v168, 0xbfb8aa3b, v168
	v_mul_f32_e32 v169, 0xbfb8aa3b, v169
	v_exp_f32_e32 v168, v168
	v_exp_f32_e32 v169, v169
	v_add_f32_e32 v168, 1.0, v168
	v_add_f32_e32 v169, 1.0, v169
	v_rcp_f32_e32 v168, v168
	v_rcp_f32_e32 v169, v169
	s_nop 0
	v_pk_mul_f32 v[166:167], v[166:167], v[168:169]
	s_nop 0
	v_add_f32_e32 v171, v166, v170
	v_mul_f32_e32 v170, v145, v145
	v_mov_b32_e32 v168, v166
	v_mov_b32_e32 v169, v145
	v_pk_add_f32 v[140:141], v[170:171], v[140:141] op_sel_hi:[0,1]
	v_pk_fma_f32 v[168:169], v[168:169], v[168:169], v[140:141]
	v_cvt_pk_bf16_f32 v140, v144, v145
	v_cvt_pk_bf16_f32 v141, v166, v167
	global_store_dwordx4 v[134:135], v[138:141], off
	v_add_f32_e32 v170, v167, v171
	s_nop 0
	v_pk_mul_f32 v[138:139], v[6:7], v[132:133] op_sel:[0,1]
	s_nop 0
	v_mul_f32_e32 v140, 0x3d372713, v138
	v_mul_f32_e32 v141, 0x3d372713, v139
	v_mul_f32_e32 v140, v138, v140
	v_mul_f32_e32 v141, v139, v141
	v_fma_f32 v140, v138, v140, v138
	v_fma_f32 v141, v139, v141, v139
	v_mul_f32_e32 v140, 0x3fcc422a, v140
	v_mul_f32_e32 v141, 0x3fcc422a, v141
	v_mul_f32_e32 v140, 0xbfb8aa3b, v140
	v_mul_f32_e32 v141, 0xbfb8aa3b, v141
	v_exp_f32_e32 v140, v140
	v_exp_f32_e32 v141, v141
	v_add_f32_e32 v140, 1.0, v140
	v_add_f32_e32 v141, 1.0, v141
	v_rcp_f32_e32 v140, v140
	v_rcp_f32_e32 v141, v141
	s_nop 0
	v_pk_mul_f32 v[138:139], v[138:139], v[140:141]
	v_mul_f32_e32 v140, v167, v167
	v_add_f32_e32 v142, v138, v170
	v_mov_b32_e32 v166, v138
	v_pk_add_f32 v[140:141], v[140:141], v[168:169] op_sel_hi:[0,1]
	v_pk_fma_f32 v[140:141], v[166:167], v[166:167], v[140:141]
	v_add_f32_e32 v166, v139, v142
	v_pk_mul_f32 v[142:143], v[8:9], v[132:133] op_sel:[0,1]
	v_cvt_pk_bf16_f32 v138, v138, v139
	v_mul_f32_e32 v144, 0x3d372713, v142
	v_mul_f32_e32 v145, 0x3d372713, v143
	v_mul_f32_e32 v144, v142, v144
	v_mul_f32_e32 v145, v143, v145
	v_fma_f32 v144, v142, v144, v142
	v_fma_f32 v145, v143, v145, v143
	v_mul_f32_e32 v144, 0x3fcc422a, v144
	v_mul_f32_e32 v145, 0x3fcc422a, v145
	v_mul_f32_e32 v144, 0xbfb8aa3b, v144
	v_mul_f32_e32 v145, 0xbfb8aa3b, v145
	v_exp_f32_e32 v144, v144
	v_exp_f32_e32 v145, v145
	v_add_f32_e32 v144, 1.0, v144
	v_add_f32_e32 v145, 1.0, v145
	v_rcp_f32_e32 v144, v144
	v_rcp_f32_e32 v145, v145
	s_nop 0
	v_pk_mul_f32 v[142:143], v[142:143], v[144:145]
	s_nop 0
	v_add_f32_e32 v167, v142, v166
	v_mul_f32_e32 v166, v139, v139
	v_mov_b32_e32 v144, v142
	v_mov_b32_e32 v145, v139
	v_pk_add_f32 v[140:141], v[166:167], v[140:141] op_sel_hi:[0,1]
	v_pk_fma_f32 v[140:141], v[144:145], v[144:145], v[140:141]
	v_pk_mul_f32 v[144:145], v[2:3], v[132:133] op_sel:[0,1]
	v_add_f32_e32 v168, v143, v167
	v_mul_f32_e32 v166, 0x3d372713, v144
	v_mul_f32_e32 v167, 0x3d372713, v145
	v_mul_f32_e32 v166, v144, v166
	v_mul_f32_e32 v167, v145, v167
	v_fma_f32 v166, v144, v166, v144
	v_fma_f32 v167, v145, v167, v145
	v_mul_f32_e32 v166, 0x3fcc422a, v166
	v_mul_f32_e32 v167, 0x3fcc422a, v167
	v_mul_f32_e32 v166, 0xbfb8aa3b, v166
	v_mul_f32_e32 v167, 0xbfb8aa3b, v167
	v_exp_f32_e32 v166, v166
	v_exp_f32_e32 v167, v167
	v_cvt_pk_bf16_f32 v139, v142, v143
	v_add_f32_e32 v166, 1.0, v166
	v_add_f32_e32 v167, 1.0, v167
	v_rcp_f32_e32 v166, v166
	v_rcp_f32_e32 v167, v167
	s_nop 0
	v_pk_mul_f32 v[144:145], v[144:145], v[166:167]
	s_nop 0
	v_add_f32_e32 v169, v144, v168
	v_mul_f32_e32 v168, v143, v143
	v_mov_b32_e32 v166, v144
	v_mov_b32_e32 v167, v143
	v_pk_add_f32 v[140:141], v[168:169], v[140:141] op_sel_hi:[0,1]
	v_pk_mul_f32 v[142:143], v[4:5], v[132:133] op_sel:[0,1]
	v_pk_fma_f32 v[166:167], v[166:167], v[166:167], v[140:141]
	v_mul_f32_e32 v141, 0x3d372713, v142
	v_mul_f32_e32 v141, v142, v141
	v_fma_f32 v141, v142, v141, v142
	v_mul_f32_e32 v141, 0x3fcc422a, v141
	v_mul_f32_e32 v141, 0xbfb8aa3b, v141
	v_exp_f32_e32 v141, v141
	v_mul_f32_e32 v174, v145, v145
	v_add_f32_e32 v168, v145, v169
	v_cvt_pk_bf16_f32 v140, v144, v145
	v_add_f32_e32 v141, 1.0, v141
	v_rcp_f32_e32 v170, v141
	v_mul_f32_e32 v141, 0x3d372713, v143
	v_mul_f32_e32 v141, v143, v141
	v_fma_f32 v141, v143, v141, v143
	v_mul_f32_e32 v141, 0x3fcc422a, v141
	v_mul_f32_e32 v141, 0xbfb8aa3b, v141
	v_exp_f32_e32 v141, v141
	v_pk_add_f32 v[166:167], v[174:175], v[166:167] op_sel_hi:[0,1]
	v_add_f32_e32 v141, 1.0, v141
	v_rcp_f32_e32 v171, v141
	s_nop 0
	v_pk_mul_f32 v[172:173], v[142:143], v[170:171]
	s_nop 0
	v_mov_b32_e32 v144, v172
	v_mov_b32_e32 v169, v173
	v_pk_fma_f32 v[144:145], v[144:145], v[144:145], v[166:167]
	v_pk_fma_f32 v[142:143], v[142:143], v[170:171], v[168:169]
	v_pk_mul_f32 v[166:167], v[172:173], v[172:173]
	v_pk_mov_b32 v[144:145], v[172:173], v[144:145] op_sel:[1,0]
	v_mov_b32_e32 v143, v167
	v_pk_add_f32 v[142:143], v[142:143], v[144:145]
	v_cvt_pk_bf16_f32 v141, v172, v173
	global_store_dwordx4 v[134:135], v[138:141], off offset:256
	v_mov_b32_e32 v134, v142
	s_nop 1
	v_permlane16_swap_b32_e32 v134, v142
	v_mov_b32_e32 v135, v143
	s_nop 1
	v_permlane16_swap_b32_e32 v135, v143
	s_waitcnt lgkmcnt(0)
	v_pk_add_f32 v[134:135], v[142:143], v[134:135]
	s_nop 0
	v_mov_b32_e32 v138, v134
	s_nop 1
	v_permlane32_swap_b32_e32 v138, v134
	v_mov_b32_e32 v139, v135
	s_nop 1
	v_permlane32_swap_b32_e32 v139, v135
	s_and_saveexec_b64 s[10:11], vcc
	s_cbranch_execz .LBB0_888
	v_lshlrev_b64 v[136:137], 7, v[136:137]
	v_lshl_add_u64 v[136:137], s[0:1], 0, v[136:137]
	s_waitcnt lgkmcnt(0)
	v_pk_add_f32 v[134:135], v[134:135], v[138:139]
	global_store_dwordx2 v[136:137], v[134:135], off

;     __device__ __forceinline__ void operator()(const pg8::f32x4 (&acc)[2][2][4][2], const pg8::Unit& u, int wr, int wc, int fr, int fq) const {
;     ...
;                     const int row = row0 + ai * 128 + m * 16;
;                     float ss = 0.f;
; #pragma unroll
;                     for (int bj = 0; bj < 2; ++bj)
; #pragma unroll
;                         for (int n = 0; n < 2; ++n)
; #pragma unroll
;                             for (int j = 0; j < 4; ++j) ss += (acc[ai][bj][m][n][j] * rs[ai][m]) * (acc[ai][bj][m][n][j] * rs[ai][m]);
;                     ss += __shfl_xor(ss, 16); ss += __shfl_xor(ss, 32);
;                     const float rstd = hasn ? rsqrtf(ss * (1.f / 64.f) + EPS) : 1.f;
.LBB0_1056:
	v_and_b32_e32 v170, 64, v226
	v_xor_b32_e32 v0, 16, v226
	v_add_u32_e32 v189, 64, v170
	v_cmp_lt_i32_e32 vcc, v0, v189
	v_pk_mul_f32 v[172:173], v[126:127], v[164:165] op_sel_hi:[1,0]
	v_pk_mul_f32 v[174:175], v[128:129], v[164:165] op_sel_hi:[1,0]
	v_cndmask_b32_e32 v0, v226, v0, vcc
	v_pk_mul_f32 v[126:127], v[172:173], v[172:173]
	v_lshlrev_b32_e32 v188, 2, v0
	v_pk_mul_f32 v[176:177], v[174:175], v[174:175]
	v_add_f32_e32 v0, v126, v127
	v_pk_mul_f32 v[128:129], v[122:123], v[164:165] op_sel_hi:[1,0]
	v_add_f32_e32 v0, v176, v0
	v_pk_mul_f32 v[178:179], v[128:129], v[128:129]
	v_add_f32_e32 v0, v177, v0
	v_pk_mul_f32 v[170:171], v[124:125], v[164:165] op_sel_hi:[1,0]
	v_add_f32_e32 v0, v178, v0
	v_pk_mul_f32 v[124:125], v[170:171], v[170:171]
	v_add_f32_e32 v0, v179, v0
	v_pk_mul_f32 v[122:123], v[118:119], v[164:165] op_sel_hi:[1,0]
	v_add_f32_e32 v0, v124, v0
	v_pk_mul_f32 v[180:181], v[122:123], v[122:123]
	v_add_f32_e32 v0, v125, v0
	v_pk_mul_f32 v[120:121], v[120:121], v[164:165] op_sel_hi:[1,0]
	v_add_f32_e32 v0, v180, v0
	v_pk_mul_f32 v[182:183], v[120:121], v[120:121]
	v_add_f32_e32 v0, v181, v0
	v_pk_mul_f32 v[118:119], v[114:115], v[164:165] op_sel_hi:[1,0]
	v_add_f32_e32 v0, v182, v0
	v_pk_mul_f32 v[114:115], v[118:119], v[118:119]
	v_add_f32_e32 v0, v183, v0
	v_pk_mul_f32 v[116:117], v[116:117], v[164:165] op_sel_hi:[1,0]
	v_add_f32_e32 v0, v114, v0
	v_pk_mul_f32 v[190:191], v[116:117], v[116:117]
	v_add_f32_e32 v0, v115, v0
	v_add_f32_e32 v0, v190, v0
	v_add_f32_e32 v0, v191, v0
	v_mov_b32_e32 v114, v0
	s_nop 1
	v_permlane16_swap_b32_e32 v114, v0
	v_xor_b32_e32 v115, 32, v226
	v_cmp_lt_i32_e32 vcc, v115, v189
	s_mov_b64 s[10:11], -1
	s_waitcnt lgkmcnt(0)
	v_add_f32_e32 v0, v0, v114
	v_cndmask_b32_e32 v115, v226, v115, vcc
	v_lshlrev_b32_e32 v189, 2, v115
	v_mov_b32_e32 v114, v0
	s_nop 1
	v_permlane32_swap_b32_e32 v114, v0
	s_and_b64 vcc, exec, s[0:1]
	s_cbranch_vccnz .LBB0_1061
	s_cmp_lt_i32 s66, 8
	s_cbranch_scc1 .LBB0_1059
	s_cmp_eq_u32 s66, 8
	s_cselect_b64 s[10:11], -1, 0
	s_cbranch_execz .LBB0_1060
	s_branch .LBB0_1061

;     __device__ __forceinline__ void operator()(const pg8::f32x4 (&acc)[2][2][4][2], const pg8::Unit& u, int wr, int wc, int fr, int fq) const {
;     ...
;                     const int row = row0 + ai * 128 + m * 16;
;                     float ss = 0.f;
; #pragma unroll
;                     for (int bj = 0; bj < 2; ++bj)
; #pragma unroll
;                         for (int n = 0; n < 2; ++n)
; #pragma unroll
;                             for (int j = 0; j < 4; ++j) ss += (acc[ai][bj][m][n][j] * rs[ai][m]) * (acc[ai][bj][m][n][j] * rs[ai][m]);
;                     ss += __shfl_xor(ss, 16); ss += __shfl_xor(ss, 32);
;                     const float rstd = hasn ? rsqrtf(ss * (1.f / 64.f) + EPS) : 1.f;
.LBB0_1079:
	v_pk_mul_f32 v[116:117], v[110:111], v[164:165] op_sel:[0,1]
	v_pk_mul_f32 v[112:113], v[112:113], v[164:165] op_sel:[0,1]
	v_pk_mul_f32 v[110:111], v[116:117], v[116:117]
	v_pk_mul_f32 v[120:121], v[112:113], v[112:113]
	v_add_f32_e32 v0, v110, v111
	v_pk_mul_f32 v[118:119], v[106:107], v[164:165] op_sel:[0,1]
	v_add_f32_e32 v0, v120, v0
	v_pk_mul_f32 v[106:107], v[118:119], v[118:119]
	v_add_f32_e32 v0, v121, v0
	v_pk_mul_f32 v[108:109], v[108:109], v[164:165] op_sel:[0,1]
	v_add_f32_e32 v0, v106, v0
	v_pk_mul_f32 v[122:123], v[108:109], v[108:109]
	v_add_f32_e32 v0, v107, v0
	v_pk_mul_f32 v[102:103], v[102:103], v[164:165] op_sel:[0,1]
	v_add_f32_e32 v0, v122, v0
	v_pk_mul_f32 v[124:125], v[102:103], v[102:103]
	v_add_f32_e32 v0, v123, v0
	v_pk_mul_f32 v[104:105], v[104:105], v[164:165] op_sel:[0,1]
	v_add_f32_e32 v0, v124, v0
	v_pk_mul_f32 v[126:127], v[104:105], v[104:105]
	v_add_f32_e32 v0, v125, v0
	v_pk_mul_f32 v[98:99], v[98:99], v[164:165] op_sel:[0,1]
	v_add_f32_e32 v0, v126, v0
	v_pk_mul_f32 v[128:129], v[98:99], v[98:99]
	v_add_f32_e32 v0, v127, v0
	v_pk_mul_f32 v[100:101], v[100:101], v[164:165] op_sel:[0,1]
	v_add_f32_e32 v0, v128, v0
	v_pk_mul_f32 v[164:165], v[100:101], v[100:101]
	v_add_f32_e32 v0, v129, v0
	v_add_f32_e32 v0, v164, v0
	v_add_f32_e32 v0, v165, v0
	v_mov_b32_e32 v106, v0
	s_nop 1
	v_permlane16_swap_b32_e32 v106, v0
	s_and_b64 vcc, exec, s[0:1]
	s_mov_b64 s[16:17], -1
	s_waitcnt lgkmcnt(0)
	v_add_f32_e32 v0, v0, v106
	v_mov_b32_e32 v106, v0
	s_nop 1
	v_permlane32_swap_b32_e32 v106, v0
	s_cbranch_vccnz .LBB0_1084
	s_cmp_lt_i32 s66, 8
	s_cbranch_scc1 .LBB0_1082
	s_cmp_eq_u32 s66, 8
	s_cselect_b64 s[16:17], -1, 0
	s_cbranch_execz .LBB0_1083
	s_branch .LBB0_1084

;     __device__ __forceinline__ void operator()(const pg8::f32x4 (&acc)[2][2][4][2], const pg8::Unit& u, int wr, int wc, int fr, int fq) const {
;     ...
;                     const int row = row0 + ai * 128 + m * 16;
;                     float ss = 0.f;
; #pragma unroll
;                     for (int bj = 0; bj < 2; ++bj)
; #pragma unroll
;                         for (int n = 0; n < 2; ++n)
; #pragma unroll
;                             for (int j = 0; j < 4; ++j) ss += (acc[ai][bj][m][n][j] * rs[ai][m]) * (acc[ai][bj][m][n][j] * rs[ai][m]);
;                     ss += __shfl_xor(ss, 16); ss += __shfl_xor(ss, 32);
;                     const float rstd = hasn ? rsqrtf(ss * (1.f / 64.f) + EPS) : 1.f;
.LBB0_1102:
	v_pk_mul_f32 v[98:99], v[94:95], v[162:163] op_sel_hi:[1,0]
	v_pk_mul_f32 v[96:97], v[96:97], v[162:163] op_sel_hi:[1,0]
	v_pk_mul_f32 v[94:95], v[98:99], v[98:99]
	v_pk_mul_f32 v[102:103], v[96:97], v[96:97]
	v_add_f32_e32 v0, v94, v95
	v_pk_mul_f32 v[100:101], v[90:91], v[162:163] op_sel_hi:[1,0]
	v_add_f32_e32 v0, v102, v0
	v_pk_mul_f32 v[90:91], v[100:101], v[100:101]
	v_add_f32_e32 v0, v103, v0
	v_pk_mul_f32 v[92:93], v[92:93], v[162:163] op_sel_hi:[1,0]
	v_add_f32_e32 v0, v90, v0
	v_pk_mul_f32 v[104:105], v[92:93], v[92:93]
	v_add_f32_e32 v0, v91, v0
	v_pk_mul_f32 v[86:87], v[86:87], v[162:163] op_sel_hi:[1,0]
	v_add_f32_e32 v0, v104, v0
	v_pk_mul_f32 v[106:107], v[86:87], v[86:87]
	v_add_f32_e32 v0, v105, v0
	v_pk_mul_f32 v[88:89], v[88:89], v[162:163] op_sel_hi:[1,0]
	v_add_f32_e32 v0, v106, v0
	v_pk_mul_f32 v[108:109], v[88:89], v[88:89]
	v_add_f32_e32 v0, v107, v0
	v_pk_mul_f32 v[82:83], v[82:83], v[162:163] op_sel_hi:[1,0]
	v_add_f32_e32 v0, v108, v0
	v_pk_mul_f32 v[110:111], v[82:83], v[82:83]
	v_add_f32_e32 v0, v109, v0
	v_pk_mul_f32 v[84:85], v[84:85], v[162:163] op_sel_hi:[1,0]
	v_add_f32_e32 v0, v110, v0
	v_pk_mul_f32 v[112:113], v[84:85], v[84:85]
	v_add_f32_e32 v0, v111, v0
	v_add_f32_e32 v0, v112, v0
	v_add_f32_e32 v0, v113, v0
	v_mov_b32_e32 v90, v0
	s_nop 1
	v_permlane16_swap_b32_e32 v90, v0
	s_and_b64 vcc, exec, s[0:1]
	s_mov_b64 s[16:17], -1
	s_waitcnt lgkmcnt(0)
	v_add_f32_e32 v0, v0, v90
	v_mov_b32_e32 v90, v0
	s_nop 1
	v_permlane32_swap_b32_e32 v90, v0
	s_cbranch_vccnz .LBB0_1107
	s_cmp_lt_i32 s66, 8
	s_cbranch_scc1 .LBB0_1105
	s_cmp_eq_u32 s66, 8
	s_cselect_b64 s[16:17], -1, 0
	s_cbranch_execz .LBB0_1106
	s_branch .LBB0_1107

;     __device__ __forceinline__ void operator()(const pg8::f32x4 (&acc)[2][2][4][2], const pg8::Unit& u, int wr, int wc, int fr, int fq) const {
;     ...
;                     const int row = row0 + ai * 128 + m * 16;
;                     float ss = 0.f;
; #pragma unroll
;                     for (int bj = 0; bj < 2; ++bj)
; #pragma unroll
;                         for (int n = 0; n < 2; ++n)
; #pragma unroll
;                             for (int j = 0; j < 4; ++j) ss += (acc[ai][bj][m][n][j] * rs[ai][m]) * (acc[ai][bj][m][n][j] * rs[ai][m]);
;                     ss += __shfl_xor(ss, 16); ss += __shfl_xor(ss, 32);
;                     const float rstd = hasn ? rsqrtf(ss * (1.f / 64.f) + EPS) : 1.f;
.LBB0_1125:
	v_pk_mul_f32 v[82:83], v[78:79], v[162:163] op_sel:[0,1]
	v_pk_mul_f32 v[80:81], v[80:81], v[162:163] op_sel:[0,1]
	v_pk_mul_f32 v[78:79], v[82:83], v[82:83]
	v_pk_mul_f32 v[86:87], v[80:81], v[80:81]
	v_add_f32_e32 v0, v78, v79
	v_pk_mul_f32 v[84:85], v[74:75], v[162:163] op_sel:[0,1]
	v_add_f32_e32 v0, v86, v0
	v_pk_mul_f32 v[74:75], v[84:85], v[84:85]
	v_add_f32_e32 v0, v87, v0
	v_pk_mul_f32 v[76:77], v[76:77], v[162:163] op_sel:[0,1]
	v_add_f32_e32 v0, v74, v0
	v_pk_mul_f32 v[88:89], v[76:77], v[76:77]
	v_add_f32_e32 v0, v75, v0
	v_pk_mul_f32 v[70:71], v[70:71], v[162:163] op_sel:[0,1]
	v_add_f32_e32 v0, v88, v0
	v_pk_mul_f32 v[90:91], v[70:71], v[70:71]
	v_add_f32_e32 v0, v89, v0
	v_pk_mul_f32 v[72:73], v[72:73], v[162:163] op_sel:[0,1]
	v_add_f32_e32 v0, v90, v0
	v_pk_mul_f32 v[92:93], v[72:73], v[72:73]
	v_add_f32_e32 v0, v91, v0
	v_pk_mul_f32 v[66:67], v[66:67], v[162:163] op_sel:[0,1]
	v_add_f32_e32 v0, v92, v0
	v_pk_mul_f32 v[94:95], v[66:67], v[66:67]
	v_add_f32_e32 v0, v93, v0
	v_pk_mul_f32 v[68:69], v[68:69], v[162:163] op_sel:[0,1]
	v_add_f32_e32 v0, v94, v0
	v_pk_mul_f32 v[96:97], v[68:69], v[68:69]
	v_add_f32_e32 v0, v95, v0
	v_add_f32_e32 v0, v96, v0
	v_add_f32_e32 v0, v97, v0
	v_mov_b32_e32 v74, v0
	s_nop 1
	v_permlane16_swap_b32_e32 v74, v0
	s_and_b64 vcc, exec, s[0:1]
	s_mov_b64 s[16:17], -1
	s_waitcnt lgkmcnt(0)
	v_add_f32_e32 v0, v0, v74
	v_mov_b32_e32 v74, v0
	s_nop 1
	v_permlane32_swap_b32_e32 v74, v0
	s_cbranch_vccnz .LBB0_1130
	s_cmp_lt_i32 s66, 8
	s_cbranch_scc1 .LBB0_1128
	s_cmp_eq_u32 s66, 8
	s_cselect_b64 s[16:17], -1, 0
	s_cbranch_execz .LBB0_1129
	s_branch .LBB0_1130

;     __device__ __forceinline__ void operator()(const pg8::f32x4 (&acc)[2][2][4][2], const pg8::Unit& u, int wr, int wc, int fr, int fq) const {
;     ...
;                     const int row = row0 + ai * 128 + m * 16;
;                     float ss = 0.f;
; #pragma unroll
;                     for (int bj = 0; bj < 2; ++bj)
; #pragma unroll
;                         for (int n = 0; n < 2; ++n)
; #pragma unroll
;                             for (int j = 0; j < 4; ++j) ss += (acc[ai][bj][m][n][j] * rs[ai][m]) * (acc[ai][bj][m][n][j] * rs[ai][m]);
;                     ss += __shfl_xor(ss, 16); ss += __shfl_xor(ss, 32);
;                     const float rstd = hasn ? rsqrtf(ss * (1.f / 64.f) + EPS) : 1.f;
.LBB0_1148:
	v_pk_mul_f32 v[66:67], v[62:63], v[160:161] op_sel_hi:[1,0]
	v_pk_mul_f32 v[64:65], v[64:65], v[160:161] op_sel_hi:[1,0]
	v_pk_mul_f32 v[62:63], v[66:67], v[66:67]
	v_pk_mul_f32 v[70:71], v[64:65], v[64:65]
	v_add_f32_e32 v0, v62, v63
	v_pk_mul_f32 v[68:69], v[58:59], v[160:161] op_sel_hi:[1,0]
	v_add_f32_e32 v0, v70, v0
	v_pk_mul_f32 v[58:59], v[68:69], v[68:69]
	v_add_f32_e32 v0, v71, v0
	v_pk_mul_f32 v[60:61], v[60:61], v[160:161] op_sel_hi:[1,0]
	v_add_f32_e32 v0, v58, v0
	v_pk_mul_f32 v[72:73], v[60:61], v[60:61]
	v_add_f32_e32 v0, v59, v0
	v_pk_mul_f32 v[54:55], v[54:55], v[160:161] op_sel_hi:[1,0]
	v_add_f32_e32 v0, v72, v0
	v_pk_mul_f32 v[74:75], v[54:55], v[54:55]
	v_add_f32_e32 v0, v73, v0
	v_pk_mul_f32 v[56:57], v[56:57], v[160:161] op_sel_hi:[1,0]
	v_add_f32_e32 v0, v74, v0
	v_pk_mul_f32 v[76:77], v[56:57], v[56:57]
	v_add_f32_e32 v0, v75, v0
	v_pk_mul_f32 v[50:51], v[50:51], v[160:161] op_sel_hi:[1,0]
	v_add_f32_e32 v0, v76, v0
	v_pk_mul_f32 v[78:79], v[50:51], v[50:51]
	v_add_f32_e32 v0, v77, v0
	v_pk_mul_f32 v[52:53], v[52:53], v[160:161] op_sel_hi:[1,0]
	v_add_f32_e32 v0, v78, v0
	v_pk_mul_f32 v[80:81], v[52:53], v[52:53]
	v_add_f32_e32 v0, v79, v0
	v_add_f32_e32 v0, v80, v0
	v_add_f32_e32 v0, v81, v0
	v_mov_b32_e32 v58, v0
	s_nop 1
	v_permlane16_swap_b32_e32 v58, v0
	s_and_b64 vcc, exec, s[0:1]
	s_mov_b64 s[16:17], -1
	s_waitcnt lgkmcnt(0)
	v_add_f32_e32 v0, v0, v58
	v_mov_b32_e32 v58, v0
	s_nop 1
	v_permlane32_swap_b32_e32 v58, v0
	s_cbranch_vccnz .LBB0_1153
	s_cmp_lt_i32 s66, 8
	s_cbranch_scc1 .LBB0_1151
	s_cmp_eq_u32 s66, 8
	s_cselect_b64 s[16:17], -1, 0
	s_cbranch_execz .LBB0_1152
	s_branch .LBB0_1153

;     __device__ __forceinline__ void operator()(const pg8::f32x4 (&acc)[2][2][4][2], const pg8::Unit& u, int wr, int wc, int fr, int fq) const {
;     ...
;                     const int row = row0 + ai * 128 + m * 16;
;                     float ss = 0.f;
; #pragma unroll
;                     for (int bj = 0; bj < 2; ++bj)
; #pragma unroll
;                         for (int n = 0; n < 2; ++n)
; #pragma unroll
;                             for (int j = 0; j < 4; ++j) ss += (acc[ai][bj][m][n][j] * rs[ai][m]) * (acc[ai][bj][m][n][j] * rs[ai][m]);
;                     ss += __shfl_xor(ss, 16); ss += __shfl_xor(ss, 32);
;                     const float rstd = hasn ? rsqrtf(ss * (1.f / 64.f) + EPS) : 1.f;
.LBB0_1171:
	v_pk_mul_f32 v[50:51], v[46:47], v[160:161] op_sel:[0,1]
	v_pk_mul_f32 v[48:49], v[48:49], v[160:161] op_sel:[0,1]
	v_pk_mul_f32 v[46:47], v[50:51], v[50:51]
	v_pk_mul_f32 v[54:55], v[48:49], v[48:49]
	v_add_f32_e32 v0, v46, v47
	v_pk_mul_f32 v[52:53], v[42:43], v[160:161] op_sel:[0,1]
	v_add_f32_e32 v0, v54, v0
	v_pk_mul_f32 v[42:43], v[52:53], v[52:53]
	v_add_f32_e32 v0, v55, v0
	v_pk_mul_f32 v[44:45], v[44:45], v[160:161] op_sel:[0,1]
	v_add_f32_e32 v0, v42, v0
	v_pk_mul_f32 v[56:57], v[44:45], v[44:45]
	v_add_f32_e32 v0, v43, v0
	v_pk_mul_f32 v[38:39], v[38:39], v[160:161] op_sel:[0,1]
	v_add_f32_e32 v0, v56, v0
	v_pk_mul_f32 v[58:59], v[38:39], v[38:39]
	v_add_f32_e32 v0, v57, v0
	v_pk_mul_f32 v[40:41], v[40:41], v[160:161] op_sel:[0,1]
	v_add_f32_e32 v0, v58, v0
	v_pk_mul_f32 v[60:61], v[40:41], v[40:41]
	v_add_f32_e32 v0, v59, v0
	v_pk_mul_f32 v[34:35], v[34:35], v[160:161] op_sel:[0,1]
	v_add_f32_e32 v0, v60, v0
	v_pk_mul_f32 v[62:63], v[34:35], v[34:35]
	v_add_f32_e32 v0, v61, v0
	v_pk_mul_f32 v[36:37], v[36:37], v[160:161] op_sel:[0,1]
	v_add_f32_e32 v0, v62, v0
	v_pk_mul_f32 v[64:65], v[36:37], v[36:37]
	v_add_f32_e32 v0, v63, v0
	v_add_f32_e32 v0, v64, v0
	v_add_f32_e32 v0, v65, v0
	v_mov_b32_e32 v42, v0
	s_nop 1
	v_permlane16_swap_b32_e32 v42, v0
	s_and_b64 vcc, exec, s[0:1]
	s_mov_b64 s[16:17], -1
	s_waitcnt lgkmcnt(0)
	v_add_f32_e32 v0, v0, v42
	v_mov_b32_e32 v42, v0
	s_nop 1
	v_permlane32_swap_b32_e32 v42, v0
	s_cbranch_vccnz .LBB0_1176
	s_cmp_lt_i32 s66, 8
	s_cbranch_scc1 .LBB0_1174
	s_cmp_eq_u32 s66, 8
	s_cselect_b64 s[16:17], -1, 0
	s_cbranch_execz .LBB0_1175
	s_branch .LBB0_1176

;     __device__ __forceinline__ void operator()(const pg8::f32x4 (&acc)[2][2][4][2], const pg8::Unit& u, int wr, int wc, int fr, int fq) const {
;     ...
;                     const int row = row0 + ai * 128 + m * 16;
;                     float ss = 0.f;
; #pragma unroll
;                     for (int bj = 0; bj < 2; ++bj)
; #pragma unroll
;                         for (int n = 0; n < 2; ++n)
; #pragma unroll
;                             for (int j = 0; j < 4; ++j) ss += (acc[ai][bj][m][n][j] * rs[ai][m]) * (acc[ai][bj][m][n][j] * rs[ai][m]);
;                     ss += __shfl_xor(ss, 16); ss += __shfl_xor(ss, 32);
;                     const float rstd = hasn ? rsqrtf(ss * (1.f / 64.f) + EPS) : 1.f;
.LBB0_1194:
	v_pk_mul_f32 v[34:35], v[30:31], v[132:133] op_sel_hi:[1,0]
	v_pk_mul_f32 v[32:33], v[32:33], v[132:133] op_sel_hi:[1,0]
	v_pk_mul_f32 v[30:31], v[34:35], v[34:35]
	v_pk_mul_f32 v[38:39], v[32:33], v[32:33]
	v_add_f32_e32 v0, v30, v31
	v_pk_mul_f32 v[36:37], v[26:27], v[132:133] op_sel_hi:[1,0]
	v_add_f32_e32 v0, v38, v0
	v_pk_mul_f32 v[26:27], v[36:37], v[36:37]
	v_add_f32_e32 v0, v39, v0
	v_pk_mul_f32 v[28:29], v[28:29], v[132:133] op_sel_hi:[1,0]
	v_add_f32_e32 v0, v26, v0
	v_pk_mul_f32 v[40:41], v[28:29], v[28:29]
	v_add_f32_e32 v0, v27, v0
	v_pk_mul_f32 v[22:23], v[22:23], v[132:133] op_sel_hi:[1,0]
	v_add_f32_e32 v0, v40, v0
	v_pk_mul_f32 v[42:43], v[22:23], v[22:23]
	v_add_f32_e32 v0, v41, v0
	v_pk_mul_f32 v[24:25], v[24:25], v[132:133] op_sel_hi:[1,0]
	v_add_f32_e32 v0, v42, v0
	v_pk_mul_f32 v[44:45], v[24:25], v[24:25]
	v_add_f32_e32 v0, v43, v0
	v_pk_mul_f32 v[18:19], v[18:19], v[132:133] op_sel_hi:[1,0]
	v_add_f32_e32 v0, v44, v0
	v_pk_mul_f32 v[46:47], v[18:19], v[18:19]
	v_add_f32_e32 v0, v45, v0
	v_pk_mul_f32 v[20:21], v[20:21], v[132:133] op_sel_hi:[1,0]
	v_add_f32_e32 v0, v46, v0
	v_pk_mul_f32 v[48:49], v[20:21], v[20:21]
	v_add_f32_e32 v0, v47, v0
	v_add_f32_e32 v0, v48, v0
	v_add_f32_e32 v0, v49, v0
	v_mov_b32_e32 v26, v0
	s_nop 1
	v_permlane16_swap_b32_e32 v26, v0
	s_and_b64 vcc, exec, s[0:1]
	s_mov_b64 s[16:17], -1
	s_waitcnt lgkmcnt(0)
	v_add_f32_e32 v0, v0, v26
	v_mov_b32_e32 v26, v0
	s_nop 1
	v_permlane32_swap_b32_e32 v26, v0
	s_cbranch_vccnz .LBB0_1199
	s_cmp_lt_i32 s66, 8
	s_cbranch_scc1 .LBB0_1197
	s_cmp_eq_u32 s66, 8
	s_cselect_b64 s[16:17], -1, 0
	s_cbranch_execz .LBB0_1198
	s_branch .LBB0_1199

;     __device__ __forceinline__ void operator()(const pg8::f32x4 (&acc)[2][2][4][2], const pg8::Unit& u, int wr, int wc, int fr, int fq) const {
;     ...
;                     const int row = row0 + ai * 128 + m * 16;
;                     float ss = 0.f;
; #pragma unroll
;                     for (int bj = 0; bj < 2; ++bj)
; #pragma unroll
;                         for (int n = 0; n < 2; ++n)
; #pragma unroll
;                             for (int j = 0; j < 4; ++j) ss += (acc[ai][bj][m][n][j] * rs[ai][m]) * (acc[ai][bj][m][n][j] * rs[ai][m]);
;                     ss += __shfl_xor(ss, 16); ss += __shfl_xor(ss, 32);
;                     const float rstd = hasn ? rsqrtf(ss * (1.f / 64.f) + EPS) : 1.f;
.LBB0_1217:
	v_pk_mul_f32 v[18:19], v[14:15], v[132:133] op_sel:[0,1]
	v_pk_mul_f32 v[16:17], v[16:17], v[132:133] op_sel:[0,1]
	v_pk_mul_f32 v[14:15], v[18:19], v[18:19]
	v_pk_mul_f32 v[22:23], v[16:17], v[16:17]
	v_add_f32_e32 v0, v14, v15
	v_pk_mul_f32 v[20:21], v[10:11], v[132:133] op_sel:[0,1]
	v_add_f32_e32 v0, v22, v0
	v_pk_mul_f32 v[10:11], v[20:21], v[20:21]
	v_add_f32_e32 v0, v23, v0
	v_pk_mul_f32 v[12:13], v[12:13], v[132:133] op_sel:[0,1]
	v_add_f32_e32 v0, v10, v0
	v_pk_mul_f32 v[24:25], v[12:13], v[12:13]
	v_add_f32_e32 v0, v11, v0
	v_pk_mul_f32 v[6:7], v[6:7], v[132:133] op_sel:[0,1]
	v_add_f32_e32 v0, v24, v0
	v_pk_mul_f32 v[26:27], v[6:7], v[6:7]
	v_add_f32_e32 v0, v25, v0
	v_pk_mul_f32 v[8:9], v[8:9], v[132:133] op_sel:[0,1]
	v_add_f32_e32 v0, v26, v0
	v_pk_mul_f32 v[28:29], v[8:9], v[8:9]
	v_add_f32_e32 v0, v27, v0
	v_pk_mul_f32 v[2:3], v[2:3], v[132:133] op_sel:[0,1]
	v_add_f32_e32 v0, v28, v0
	v_pk_mul_f32 v[30:31], v[2:3], v[2:3]
	v_add_f32_e32 v0, v29, v0
	v_pk_mul_f32 v[4:5], v[4:5], v[132:133] op_sel:[0,1]
	v_add_f32_e32 v0, v30, v0
	v_pk_mul_f32 v[32:33], v[4:5], v[4:5]
	v_add_f32_e32 v0, v31, v0
	v_add_f32_e32 v0, v32, v0
	v_add_f32_e32 v0, v33, v0
	v_mov_b32_e32 v10, v0
	s_nop 1
	v_permlane16_swap_b32_e32 v10, v0
	s_and_b64 vcc, exec, s[0:1]
	s_mov_b64 s[0:1], -1
	s_waitcnt lgkmcnt(0)
	v_add_f32_e32 v0, v0, v10
	v_mov_b32_e32 v10, v0
	s_nop 1
	v_permlane32_swap_b32_e32 v10, v0
	s_cbranch_vccnz .LBB0_1222
	s_cmp_lt_i32 s66, 8
	s_cbranch_scc1 .LBB0_1220
	s_cmp_eq_u32 s66, 8
	s_cselect_b64 s[0:1], -1, 0
	s_cbranch_execz .LBB0_1221
	s_branch .LBB0_1222

;     __device__ __forceinline__ void operator()(const pg8::f32x4 (&acc)[2][2][4][2], const pg8::Unit& u, int wr, int wc, int fr, int fq) const {
;     ...
;                     ss += (a.x * a.x + a.y * a.y) + (a.z * a.z + a.w * a.w) + (b.x * b.x + b.y * b.y) + (b.z * b.z + b.w * b.w);
;                 }
;                 ss += __shfl_xor(ss, 16); ss += __shfl_xor(ss, 32);
;                 if (fq_ == 0) xch[(ai * 128 + wr * 64 + m * 16 + fr_) * 4 + wc] = ss;
.LBB0_1276:
	v_mul_f32_e32 v126, v126, v126
	v_fmac_f32_e32 v126, v127, v127
	v_mul_f32_e32 v127, v129, v129
	v_fmac_f32_e32 v127, v128, v128
	v_mul_f32_e32 v122, v122, v122
	v_mul_f32_e32 v118, v118, v118
	v_add_f32_e32 v126, v127, v126
	v_fmac_f32_e32 v122, v123, v123
	v_mul_f32_e32 v123, v124, v124
	v_fmac_f32_e32 v118, v119, v119
	v_mul_f32_e32 v119, v121, v121
	v_add_f32_e32 v122, v122, v126
	v_fmac_f32_e32 v123, v125, v125
	v_and_b32_e32 v124, 64, v226
	v_fmac_f32_e32 v119, v120, v120
	v_mul_f32_e32 v114, v114, v114
	v_add_f32_e32 v122, v123, v122
	v_xor_b32_e32 v123, 16, v226
	v_add_u32_e32 v124, 64, v124
	v_add_f32_e32 v118, v119, v118
	v_fmac_f32_e32 v114, v115, v115
	v_mul_f32_e32 v115, v116, v116
	v_cmp_lt_i32_e32 vcc, v123, v124
	v_add_f32_e32 v114, v114, v118
	v_fmac_f32_e32 v115, v117, v117
	v_cndmask_b32_e32 v123, v226, v123, vcc
	v_add_f32_e32 v114, v115, v114
	v_lshlrev_b32_e32 v146, 2, v123
	v_add_f32_e32 v114, v122, v114
	v_mov_b32_e32 v115, v114
	s_nop 1
	v_permlane16_swap_b32_e32 v115, v114
	v_xor_b32_e32 v116, 32, v226
	v_cmp_lt_i32_e32 vcc, v116, v124
	v_cmp_eq_u32_e64 s[10:11], 0, v188
	v_lshl_add_u32 v147, v189, 4, s83
	v_cndmask_b32_e32 v116, v226, v116, vcc
	v_lshlrev_b32_e32 v148, 2, v116
	s_waitcnt lgkmcnt(0)
	v_add_f32_e32 v114, v114, v115
	v_mov_b32_e32 v115, v114
	s_nop 1
	v_permlane32_swap_b32_e32 v115, v114
	s_and_saveexec_b64 s[30:31], s[10:11]
	s_cbranch_execz .LBB0_1278
	s_waitcnt lgkmcnt(0)
	v_add_f32_e32 v114, v114, v115
	ds_write_b32 v147, v114
